# gdn stage 2 (A and P matrices) hand-written: batched LDS operand reads, transposed products, 8-byte LDS stores
# baseline (speedup 1.0000x reference)
; #define LAS __attribute__((address_space(3)))
; __device__ __forceinline__ void gdn_unit(const Ctx& X, LAS unsigned char* hl, int b, int c, int h, int tid_h, int w4, int lane, int layer) {
;     ...
;         const float G63 = Gs[63];
; #pragma unroll
;         for (int rs = 0; rs < 2; ++rs) {
;             const int i = i0 + 32 * rs;
;             const float bi = Bs[i], Gi = Gs[i];
;             float y[3][8];
; #pragma unroll
;             for (int tn = 0; tn < 3; ++tn) {
; #pragma unroll
;                 for (int e = 0; e < 8; ++e) y[tn][e] = 0.f;
; #pragma unroll
;                 for (int k = 0; k < 4; ++k) { float x8[8]; unpack8(*(const LAS u32x4*)(RAW + (tn * 67 + i + k) * 64 + cseg * 8), x8);
;                     y[tn][0] += wq[tn][k][0].x * x8[0]; y[tn][1] += wq[tn][k][0].y * x8[1]; y[tn][2] += wq[tn][k][0].z * x8[2]; y[tn][3] += wq[tn][k][0].w * x8[3];
;                     y[tn][4] += wq[tn][k][1].x * x8[4]; y[tn][5] += wq[tn][k][1].y * x8[5]; y[tn][6] += wq[tn][k][1].z * x8[6]; y[tn][7] += wq[tn][k][1].w * x8[7]; }
.LpfG_done:
	v_add_u32_e32 v193, v182, v156
	v_cndmask_b32_e32 v102, v230, v102, vcc
	v_lshlrev_b32_e32 v197, 2, v102
	v_xor_b32_e32 v102, 2, v230
	v_cmp_lt_i32_e32 vcc, v102, v103
	v_add_u32_e32 v192, v189, v156
	v_add_u32_e32 v155, v183, v156
	v_add_u32_e32 v133, v181, v156
	v_lshl_add_u32 v156, v191, 7, v135
	ds_read_b32 v194, v185 offset:252
	v_cndmask_b32_e32 v102, v230, v102, vcc
	ds_read_b128 v[106:109], v156
	ds_read_b128 v[112:115], v156 offset:128
	v_lshlrev_b32_e32 v196, 2, v102
	v_xor_b32_e32 v102, 4, v230
	v_cmp_lt_i32_e32 vcc, v102, v103
	s_waitcnt lgkmcnt(1)
	v_lshlrev_b32_e32 v104, 16, v106
	s_waitcnt lgkmcnt(0)
	v_lshlrev_b32_e32 v105, 16, v112
	v_cndmask_b32_e32 v102, v230, v102, vcc
	v_lshlrev_b32_e32 v195, 2, v102
	v_lshlrev_b32_e32 v102, 2, v191
	v_add_u32_e32 v198, v188, v102
	v_add_u32_e32 v199, v185, v102
	v_mov_b32_e32 v102, v66
	v_mov_b32_e32 v103, v74
	v_pk_mul_f32 v[134:135], v[102:103], v[104:105]
	v_and_b32_e32 v105, 0xffff0000, v112
	v_and_b32_e32 v104, 0xffff0000, v106
	v_mov_b32_e32 v74, v67
	v_pk_mul_f32 v[136:137], v[74:75], v[104:105]
	v_lshlrev_b32_e32 v105, 16, v107
	v_lshlrev_b32_e32 v104, 16, v113
	v_mov_b32_e32 v66, v76
	v_mov_b32_e32 v67, v68
	ds_read_b32 v200, v198
	ds_read_b32 v201, v199
	v_pk_mul_f32 v[118:119], v[66:67], v[104:105]
	v_and_b32_e32 v105, 0xffff0000, v107
	v_and_b32_e32 v104, 0xffff0000, v113
	v_mov_b32_e32 v68, v77
	ds_read_b128 v[122:125], v156 offset:256
	ds_read_b128 v[126:129], v156 offset:384
	v_pk_mul_f32 v[120:121], v[68:69], v[104:105]
	v_lshlrev_b32_e32 v77, 16, v114
	v_lshlrev_b32_e32 v76, 16, v108
	v_mov_b32_e32 v104, v58
	v_mov_b32_e32 v105, v98
	v_pk_mul_f32 v[110:111], v[104:105], v[76:77]
	v_and_b32_e32 v77, 0xffff0000, v108
	v_and_b32_e32 v76, 0xffff0000, v114
	v_mov_b32_e32 v58, v99
	v_pk_mul_f32 v[112:113], v[58:59], v[76:77]
	v_lshlrev_b32_e32 v99, 16, v109
	v_lshlrev_b32_e32 v98, 16, v115
	v_mov_b32_e32 v76, v100
	v_mov_b32_e32 v77, v60
	v_pk_mul_f32 v[106:107], v[76:77], v[98:99]
	v_and_b32_e32 v99, 0xffff0000, v109
	v_and_b32_e32 v98, 0xffff0000, v115
	v_mov_b32_e32 v60, v101
	v_pk_mul_f32 v[108:109], v[60:61], v[98:99]
	s_waitcnt lgkmcnt(0)
	v_lshlrev_b32_e32 v101, 16, v126
	v_lshlrev_b32_e32 v100, 16, v122
	v_mov_b32_e32 v98, v62
	v_mov_b32_e32 v99, v70
	v_pk_mul_f32 v[150:151], v[98:99], v[100:101]
	v_and_b32_e32 v101, 0xffff0000, v126
	v_and_b32_e32 v100, 0xffff0000, v122
	v_mov_b32_e32 v70, v63
	v_pk_mul_f32 v[162:163], v[70:71], v[100:101]
	v_lshlrev_b32_e32 v101, 16, v123
	v_lshlrev_b32_e32 v100, 16, v127
	v_mov_b32_e32 v62, v72
	v_mov_b32_e32 v63, v64
	v_pk_mul_f32 v[138:139], v[62:63], v[100:101]
	v_and_b32_e32 v101, 0xffff0000, v123
	v_and_b32_e32 v100, 0xffff0000, v127
	v_mov_b32_e32 v64, v73
	ds_read_b128 v[144:147], v156 offset:8576
	ds_read_b128 v[164:167], v156 offset:8704
	v_pk_mul_f32 v[142:143], v[64:65], v[100:101]
	v_lshlrev_b32_e32 v73, 16, v128
	v_lshlrev_b32_e32 v72, 16, v124
	v_mov_b32_e32 v100, v54
	v_mov_b32_e32 v101, v94
	v_pk_mul_f32 v[122:123], v[100:101], v[72:73]
	v_and_b32_e32 v73, 0xffff0000, v124
	v_and_b32_e32 v72, 0xffff0000, v128
	v_mov_b32_e32 v54, v95
	v_pk_mul_f32 v[126:127], v[54:55], v[72:73]
	v_lshlrev_b32_e32 v95, 16, v125
	v_lshlrev_b32_e32 v94, 16, v129
	v_mov_b32_e32 v72, v96
	v_mov_b32_e32 v73, v56
	v_pk_mul_f32 v[114:115], v[72:73], v[94:95]
	v_and_b32_e32 v95, 0xffff0000, v125
	v_and_b32_e32 v94, 0xffff0000, v129
	v_mov_b32_e32 v56, v97
	v_pk_mul_f32 v[116:117], v[56:57], v[94:95]
	s_waitcnt lgkmcnt(0)
	v_lshlrev_b32_e32 v97, 16, v164
	v_lshlrev_b32_e32 v96, 16, v144
	v_mov_b32_e32 v94, v46
	v_mov_b32_e32 v95, v50
	v_pk_mul_f32 v[168:169], v[94:95], v[96:97]
	v_and_b32_e32 v97, 0xffff0000, v164
	v_and_b32_e32 v96, 0xffff0000, v144
	v_mov_b32_e32 v50, v47
	v_pk_mul_f32 v[170:171], v[50:51], v[96:97]
	v_lshlrev_b32_e32 v97, 16, v145
	v_lshlrev_b32_e32 v96, 16, v165
	v_mov_b32_e32 v46, v52
	v_mov_b32_e32 v47, v48
	v_pk_mul_f32 v[148:149], v[46:47], v[96:97]
	v_and_b32_e32 v97, 0xffff0000, v145
	v_and_b32_e32 v96, 0xffff0000, v165
	v_mov_b32_e32 v48, v53
	ds_read_b128 v[202:205], v156 offset:8832
	ds_read_b128 v[206:209], v156 offset:8960
	v_pk_mul_f32 v[152:153], v[48:49], v[96:97]
	v_lshlrev_b32_e32 v53, 16, v166
	v_lshlrev_b32_e32 v52, 16, v146
	v_mov_b32_e32 v96, v38
	v_mov_b32_e32 v97, v90
	v_pk_mul_f32 v[140:141], v[96:97], v[52:53]
	v_and_b32_e32 v53, 0xffff0000, v146
	v_and_b32_e32 v52, 0xffff0000, v166
	v_mov_b32_e32 v38, v91
	v_pk_mul_f32 v[144:145], v[38:39], v[52:53]
	v_lshlrev_b32_e32 v91, 16, v147
	v_lshlrev_b32_e32 v90, 16, v167
	v_mov_b32_e32 v52, v92
	v_mov_b32_e32 v53, v40
	v_pk_mul_f32 v[124:125], v[52:53], v[90:91]
	v_and_b32_e32 v91, 0xffff0000, v147
	v_and_b32_e32 v90, 0xffff0000, v167
	v_mov_b32_e32 v40, v93
	v_pk_mul_f32 v[128:129], v[40:41], v[90:91]
	s_waitcnt lgkmcnt(0)
	v_lshlrev_b32_e32 v93, 16, v206
	v_lshlrev_b32_e32 v92, 16, v202
	v_mov_b32_e32 v90, v34
	v_mov_b32_e32 v91, v42
	v_pk_mul_f32 v[176:177], v[90:91], v[92:93]
	v_and_b32_e32 v93, 0xffff0000, v206
	v_and_b32_e32 v92, 0xffff0000, v202
	v_mov_b32_e32 v42, v35
	v_pk_mul_f32 v[178:179], v[42:43], v[92:93]
	v_lshlrev_b32_e32 v93, 16, v203
	v_lshlrev_b32_e32 v92, 16, v207
	v_mov_b32_e32 v34, v44
	v_mov_b32_e32 v35, v36
	v_pk_mul_f32 v[172:173], v[34:35], v[92:93]
	v_and_b32_e32 v93, 0xffff0000, v203
	v_and_b32_e32 v92, 0xffff0000, v207
	v_mov_b32_e32 v36, v45
	ds_read_b128 v[210:213], v156 offset:17152
	ds_read_b128 v[214:217], v156 offset:17280
	v_pk_mul_f32 v[174:175], v[36:37], v[92:93]
	v_lshlrev_b32_e32 v45, 16, v208
	v_lshlrev_b32_e32 v44, 16, v204
	v_mov_b32_e32 v92, v30
	v_mov_b32_e32 v93, v86
	v_pk_mul_f32 v[164:165], v[92:93], v[44:45]
	v_and_b32_e32 v45, 0xffff0000, v204
	v_and_b32_e32 v44, 0xffff0000, v208
	v_mov_b32_e32 v30, v87
	v_pk_mul_f32 v[166:167], v[30:31], v[44:45]
	v_lshlrev_b32_e32 v87, 16, v205
	v_lshlrev_b32_e32 v86, 16, v209
	v_mov_b32_e32 v44, v88
	v_mov_b32_e32 v45, v32
	v_pk_mul_f32 v[146:147], v[44:45], v[86:87]
	v_and_b32_e32 v87, 0xffff0000, v205
	v_and_b32_e32 v86, 0xffff0000, v209
	v_mov_b32_e32 v32, v89
	v_pk_mul_f32 v[88:89], v[32:33], v[86:87]
	s_waitcnt lgkmcnt(0)
; #define LAS __attribute__((address_space(3)))
; __device__ __forceinline__ float silu_acc(float x) { return x * frcp(1.0f + fexp(-x)); }
; __device__ __forceinline__ void gdn_unit(const Ctx& X, LAS unsigned char* hl, int b, int c, int h, int tid_h, int w4, int lane, int layer) {
;     ...
;             for (int tn = 0; tn < 3; ++tn) {
; #pragma unroll
;                 for (int e = 0; e < 8; ++e) y[tn][e] = 0.f;
; #pragma unroll
;                 for (int k = 0; k < 4; ++k) { float x8[8]; unpack8(*(const LAS u32x4*)(RAW + (tn * 67 + i + k) * 64 + cseg * 8), x8);
;                     y[tn][0] += wq[tn][k][0].x * x8[0]; y[tn][1] += wq[tn][k][0].y * x8[1]; y[tn][2] += wq[tn][k][0].z * x8[2]; y[tn][3] += wq[tn][k][0].w * x8[3];
;                     y[tn][4] += wq[tn][k][1].x * x8[4]; y[tn][5] += wq[tn][k][1].y * x8[5]; y[tn][6] += wq[tn][k][1].z * x8[6]; y[tn][7] += wq[tn][k][1].w * x8[7]; }
; #pragma unroll
;                 for (int e = 0; e < 8; ++e) y[tn][e] = silu_acc(y[tn][e]);
;             }
	v_lshlrev_b32_e32 v203, 16, v214
	v_lshlrev_b32_e32 v202, 16, v210
	v_mov_b32_e32 v86, v22
	v_mov_b32_e32 v87, v26
	v_pk_mul_f32 v[202:203], v[86:87], v[202:203]
	v_mov_b32_e32 v26, v23
	v_add_f32_e32 v22, 0, v202
	v_add_f32_e32 v218, v22, v203
	v_and_b32_e32 v203, 0xffff0000, v214
	v_and_b32_e32 v202, 0xffff0000, v210
	v_pk_mul_f32 v[22:23], v[26:27], v[202:203]
	v_lshlrev_b32_e32 v203, 16, v211
	v_add_f32_e32 v22, 0, v22
	v_add_f32_e32 v214, v22, v23
	v_lshlrev_b32_e32 v202, 16, v215
	v_mov_b32_e32 v22, v28
	v_mov_b32_e32 v23, v24
	v_pk_mul_f32 v[202:203], v[22:23], v[202:203]
	v_and_b32_e32 v210, 0xffff0000, v217
	v_add_f32_e32 v24, 0, v203
	v_add_f32_e32 v219, v202, v24
	v_and_b32_e32 v203, 0xffff0000, v211
	v_and_b32_e32 v202, 0xffff0000, v215
	v_mov_b32_e32 v24, v29
	v_pk_mul_f32 v[28:29], v[24:25], v[202:203]
	v_lshlrev_b32_e32 v203, 16, v216
	v_add_f32_e32 v29, 0, v29
	v_add_f32_e32 v215, v28, v29
	v_lshlrev_b32_e32 v202, 16, v212
	v_mov_b32_e32 v28, v14
	v_mov_b32_e32 v29, v82
	v_pk_mul_f32 v[202:203], v[28:29], v[202:203]
	v_and_b32_e32 v211, 0xffff0000, v213
	v_add_f32_e32 v14, 0, v202
	v_add_f32_e32 v220, v14, v203
	v_and_b32_e32 v203, 0xffff0000, v212
	v_and_b32_e32 v202, 0xffff0000, v216
	v_mov_b32_e32 v14, v83
	v_pk_mul_f32 v[82:83], v[14:15], v[202:203]
	v_lshlrev_b32_e32 v203, 16, v213
	v_add_f32_e32 v83, 0, v83
	v_add_f32_e32 v212, v82, v83
	v_lshlrev_b32_e32 v202, 16, v217
	v_mov_b32_e32 v82, v84
	v_mov_b32_e32 v83, v16
	v_pk_mul_f32 v[202:203], v[82:83], v[202:203]
	s_mov_b32 s4, 0x358637bd
	v_add_f32_e32 v16, 0, v203
	v_add_f32_e32 v216, v202, v16
	ds_read_b128 v[202:205], v156 offset:17408
	ds_read_b128 v[206:209], v156 offset:17536
	v_mov_b32_e32 v16, v85
	v_pk_mul_f32 v[84:85], v[16:17], v[210:211]
	s_waitcnt lgkmcnt(1)
	v_lshlrev_b32_e32 v210, 16, v202
	v_add_f32_e32 v85, 0, v85
	v_add_f32_e32 v213, v84, v85
	s_waitcnt lgkmcnt(0)
	v_lshlrev_b32_e32 v211, 16, v206
	v_mov_b32_e32 v84, v10
	v_mov_b32_e32 v85, v18
	v_pk_mul_f32 v[210:211], v[84:85], v[210:211]
	v_mov_b32_e32 v18, v11
	v_add_f32_e32 v10, v218, v210
	v_add_f32_e32 v217, v10, v211
	v_and_b32_e32 v211, 0xffff0000, v206
	v_and_b32_e32 v210, 0xffff0000, v202
	v_pk_mul_f32 v[10:11], v[18:19], v[210:211]
	v_lshlrev_b32_e32 v211, 16, v203
	v_add_f32_e32 v10, v214, v10
	v_add_f32_e32 v206, v10, v11
	v_lshlrev_b32_e32 v210, 16, v207
	v_mov_b32_e32 v10, v20
	v_mov_b32_e32 v11, v12
	v_pk_mul_f32 v[210:211], v[10:11], v[210:211]
	v_and_b32_e32 v203, 0xffff0000, v203
	v_add_f32_e32 v12, v211, v219
	v_add_f32_e32 v210, v210, v12
	v_and_b32_e32 v202, 0xffff0000, v207
	v_mov_b32_e32 v12, v21
	v_pk_mul_f32 v[20:21], v[12:13], v[202:203]
	v_lshlrev_b32_e32 v203, 16, v208
	v_add_f32_e32 v21, v21, v215
	v_add_f32_e32 v207, v20, v21
	v_lshlrev_b32_e32 v202, 16, v204
	v_mov_b32_e32 v20, v6
	v_mov_b32_e32 v21, v78
	v_pk_mul_f32 v[202:203], v[20:21], v[202:203]
	s_nop 0
	v_add_f32_e32 v6, v220, v202
	v_add_f32_e32 v211, v6, v203
	v_and_b32_e32 v203, 0xffff0000, v204
	v_and_b32_e32 v202, 0xffff0000, v208
	v_mov_b32_e32 v6, v79
	v_pk_mul_f32 v[78:79], v[6:7], v[202:203]
	v_lshlrev_b32_e32 v203, 16, v205
	v_add_f32_e32 v79, v79, v212
	v_add_f32_e32 v204, v78, v79
	v_lshlrev_b32_e32 v202, 16, v209
	v_mov_b32_e32 v78, v80
	v_mov_b32_e32 v79, v8
	v_pk_mul_f32 v[202:203], v[78:79], v[202:203]
	s_nop 0
	v_add_f32_e32 v8, v203, v216
	v_add_f32_e32 v208, v202, v8
	v_mul_f32_e32 v8, 0xbfb8aa3b, v217
	v_and_b32_e32 v203, 0xffff0000, v205
	v_exp_f32_e32 v205, v8
	v_and_b32_e32 v202, 0xffff0000, v209
	v_mov_b32_e32 v8, v81
	v_pk_mul_f32 v[80:81], v[8:9], v[202:203]
	v_mul_f32_e32 v203, 0xbfb8aa3b, v206
	v_exp_f32_e32 v203, v203
	v_add_f32_e32 v81, v81, v213
	v_add_f32_e32 v202, 1.0, v205
	v_add_f32_e32 v205, v80, v81
	v_add_f32_e32 v80, 1.0, v203
	v_mul_f32_e32 v203, 0xbfb8aa3b, v207
	v_mul_f32_e32 v81, 0xbfb8aa3b, v210
	v_exp_f32_e32 v203, v203
	v_exp_f32_e32 v81, v81
	v_mul_f32_e32 v209, 0xbfb8aa3b, v211
	v_rcp_f32_e32 v80, v80
	v_add_f32_e32 v203, 1.0, v203
	v_exp_f32_e32 v209, v209
	v_add_f32_e32 v81, 1.0, v81
	v_rcp_f32_e32 v203, v203
	v_rcp_f32_e32 v81, v81
	v_mul_f32_e32 v206, v206, v80
	v_add_f32_e32 v80, 1.0, v209
	v_mul_f32_e32 v203, v207, v203
	v_rcp_f32_e32 v207, v80
	v_mul_f32_e32 v80, 0xbfb8aa3b, v204
	v_mul_f32_e32 v210, v210, v81
	v_exp_f32_e32 v209, v80
	v_mov_b32_e32 v80, v134
	v_mov_b32_e32 v81, v136
	v_pk_add_f32 v[80:81], v[80:81], 0 op_sel_hi:[1,0]
	v_mov_b32_e32 v136, v135
	v_pk_add_f32 v[80:81], v[80:81], v[136:137]
	v_mov_b32_e32 v136, v168
	v_mov_b32_e32 v137, v170
	v_pk_add_f32 v[136:137], v[136:137], 0 op_sel_hi:[1,0]
	v_mov_b32_e32 v170, v169
	v_mov_b32_e32 v134, v150
	v_mov_b32_e32 v135, v162
	v_mov_b32_e32 v162, v151
	v_pk_add_f32 v[136:137], v[136:137], v[170:171]
	v_mov_b32_e32 v150, v176
	v_mov_b32_e32 v151, v178
	v_pk_add_f32 v[80:81], v[80:81], v[134:135]
	v_pk_add_f32 v[136:137], v[136:137], v[150:151]
	v_mov_b32_e32 v178, v177
	v_pk_add_f32 v[80:81], v[80:81], v[162:163]
	v_pk_add_f32 v[136:137], v[136:137], v[178:179]
	v_mul_f32_e32 v134, 0xbfb8aa3b, v80
	v_mul_f32_e32 v135, 0xbfb8aa3b, v81
	v_mul_f32_e32 v150, 0xbfb8aa3b, v136
	v_mul_f32_e32 v151, 0xbfb8aa3b, v137
	v_exp_f32_e32 v134, v134
	v_exp_f32_e32 v135, v135
	v_exp_f32_e32 v150, v150
	v_exp_f32_e32 v151, v151
	v_add_f32_e32 v134, 1.0, v134
	v_add_f32_e32 v135, 1.0, v135
	v_add_f32_e32 v150, 1.0, v150
	v_add_f32_e32 v151, 1.0, v151
	v_rcp_f32_e32 v134, v134
	v_rcp_f32_e32 v135, v135
	v_rcp_f32_e32 v150, v150
	v_rcp_f32_e32 v151, v151
	v_add_f32_e32 v162, 1.0, v209
	v_pk_mul_f32 v[134:135], v[80:81], v[134:135]
	v_rcp_f32_e32 v168, v162
	v_pk_mul_f32 v[80:81], v[136:137], v[150:151]
; #define LAS __attribute__((address_space(3)))
; __device__ __forceinline__ float silu_acc(float x) { return x * frcp(1.0f + fexp(-x)); }
; __device__ __forceinline__ void gdn_unit(const Ctx& X, LAS unsigned char* hl, int b, int c, int h, int tid_h, int w4, int lane, int layer) {
;     ...
;                 for (int k = 0; k < 4; ++k) { float x8[8]; unpack8(*(const LAS u32x4*)(RAW + (tn * 67 + i + k) * 64 + cseg * 8), x8);
;                     y[tn][0] += wq[tn][k][0].x * x8[0]; y[tn][1] += wq[tn][k][0].y * x8[1]; y[tn][2] += wq[tn][k][0].z * x8[2]; y[tn][3] += wq[tn][k][0].w * x8[3];
;                     y[tn][4] += wq[tn][k][1].x * x8[4]; y[tn][5] += wq[tn][k][1].y * x8[5]; y[tn][6] += wq[tn][k][1].z * x8[6]; y[tn][7] += wq[tn][k][1].w * x8[7]; }
; #pragma unroll
;                 for (int e = 0; e < 8; ++e) y[tn][e] = silu_acc(y[tn][e]);
;             }
;             float sq = 0.f, sk = 0.f;
; #pragma unroll
;             for (int e = 0; e < 8; ++e) { sq += y[0][e] * y[0][e]; sk += y[1][e] * y[1][e]; }
;             sq += __shfl_xor(sq, 1); sq += __shfl_xor(sq, 2); sq += __shfl_xor(sq, 4);
;             sk += __shfl_xor(sk, 1); sk += __shfl_xor(sk, 2); sk += __shfl_xor(sk, 4);
	v_mov_b32_e32 v136, v121
	v_mov_b32_e32 v137, v119
	v_pk_add_f32 v[136:137], v[136:137], 0 op_sel_hi:[1,0]
	v_mov_b32_e32 v121, v118
	v_pk_add_f32 v[118:119], v[120:121], v[136:137]
	v_mov_b32_e32 v120, v143
	v_mov_b32_e32 v121, v139
	v_pk_add_f32 v[118:119], v[120:121], v[118:119]
	v_mov_b32_e32 v143, v138
	v_pk_add_f32 v[118:119], v[142:143], v[118:119]
	v_mov_b32_e32 v139, v149
	v_mul_f32_e32 v120, 0xbfb8aa3b, v119
	v_exp_f32_e32 v136, v120
	v_mul_f32_e32 v120, 0xbfb8aa3b, v118
	v_exp_f32_e32 v138, v120
	v_mov_b32_e32 v142, v175
	v_add_f32_e32 v136, 1.0, v136
	v_rcp_f32_e32 v137, v136
	v_add_f32_e32 v136, 1.0, v138
	v_mov_b32_e32 v138, v153
	v_pk_add_f32 v[138:139], v[138:139], 0 op_sel_hi:[1,0]
	v_mov_b32_e32 v153, v148
	v_pk_add_f32 v[138:139], v[152:153], v[138:139]
	v_mov_b32_e32 v143, v173
	v_pk_add_f32 v[138:139], v[142:143], v[138:139]
	v_mov_b32_e32 v175, v172
	v_pk_add_f32 v[138:139], v[174:175], v[138:139]
	v_rcp_f32_e32 v136, v136
	v_mul_f32_e32 v142, 0xbfb8aa3b, v139
	v_exp_f32_e32 v142, v142
	v_mul_f32_e32 v143, 0xbfb8aa3b, v138
	v_exp_f32_e32 v143, v143
	v_pk_mul_f32 v[118:119], v[118:119], v[136:137]
	v_add_f32_e32 v136, 1.0, v142
	v_rcp_f32_e32 v137, v136
	v_add_f32_e32 v136, 1.0, v143
	v_pk_mov_b32 v[142:143], v[112:113], v[110:111] op_sel:[1,0]
	v_mov_b32_e32 v113, v111
	v_pk_add_f32 v[142:143], v[142:143], 0 op_sel_hi:[1,0]
	v_rcp_f32_e32 v136, v136
	v_pk_add_f32 v[110:111], v[112:113], v[142:143]
	v_pk_mov_b32 v[112:113], v[126:127], v[122:123] op_sel:[1,0]
	v_mov_b32_e32 v127, v123
	v_pk_add_f32 v[110:111], v[112:113], v[110:111]
	v_mov_b32_e32 v143, v107
	v_pk_add_f32 v[112:113], v[126:127], v[110:111]
	v_pk_mul_f32 v[162:163], v[134:135], v[134:135]
	v_mul_f32_e32 v110, 0xbfb8aa3b, v113
	v_exp_f32_e32 v110, v110
	v_mul_f32_e32 v111, 0xbfb8aa3b, v112
	v_exp_f32_e32 v111, v111
	v_pk_mul_f32 v[120:121], v[80:81], v[80:81]
	v_add_f32_e32 v110, 1.0, v110
	v_rcp_f32_e32 v123, v110
	v_add_f32_e32 v110, 1.0, v111
	v_rcp_f32_e32 v122, v110
	v_pk_mul_f32 v[110:111], v[138:139], v[136:137]
	v_pk_mov_b32 v[138:139], v[166:167], v[164:165] op_sel:[1,0]
	v_mov_b32_e32 v167, v165
	v_pk_mul_f32 v[112:113], v[112:113], v[122:123]
	v_pk_mov_b32 v[122:123], v[144:145], v[140:141] op_sel:[1,0]
	v_mov_b32_e32 v145, v141
	v_pk_add_f32 v[122:123], v[122:123], 0 op_sel_hi:[1,0]
	v_pk_mul_f32 v[126:127], v[118:119], v[118:119]
	v_pk_add_f32 v[122:123], v[144:145], v[122:123]
	v_pk_mul_f32 v[136:137], v[110:111], v[110:111]
	v_pk_add_f32 v[122:123], v[138:139], v[122:123]
	v_rcp_f32_e32 v202, v202
	v_pk_add_f32 v[122:123], v[166:167], v[122:123]
	v_mul_f32_e32 v202, v217, v202
	v_mul_f32_e32 v138, 0xbfb8aa3b, v123
	v_exp_f32_e32 v140, v138
	v_mul_f32_e32 v138, 0xbfb8aa3b, v122
	v_exp_f32_e32 v142, v138
	v_pk_mul_f32 v[138:139], v[112:113], v[112:113]
	v_add_f32_e32 v140, 1.0, v140
	v_rcp_f32_e32 v141, v140
	v_add_f32_e32 v140, 1.0, v142
	v_mov_b32_e32 v142, v109
	v_pk_add_f32 v[142:143], v[142:143], 0 op_sel_hi:[1,0]
	v_mov_b32_e32 v109, v106
	v_pk_add_f32 v[106:107], v[108:109], v[142:143]
	v_mov_b32_e32 v108, v117
	v_mov_b32_e32 v109, v115
	v_pk_add_f32 v[106:107], v[108:109], v[106:107]
	v_mov_b32_e32 v117, v114
	v_pk_add_f32 v[106:107], v[116:117], v[106:107]
	v_rcp_f32_e32 v140, v140
	v_mul_f32_e32 v108, 0xbfb8aa3b, v107
	v_exp_f32_e32 v108, v108
	v_mul_f32_e32 v109, 0xbfb8aa3b, v106
	v_exp_f32_e32 v114, v109
	v_mov_b32_e32 v115, v125
	v_add_f32_e32 v108, 1.0, v108
	v_rcp_f32_e32 v109, v108
	v_add_f32_e32 v108, 1.0, v114
	v_mov_b32_e32 v114, v129
	v_pk_add_f32 v[114:115], v[114:115], 0 op_sel_hi:[1,0]
	v_mov_b32_e32 v129, v124
	v_pk_mul_f32 v[116:117], v[122:123], v[140:141]
	v_pk_add_f32 v[114:115], v[128:129], v[114:115]
	v_mov_b32_e32 v122, v89
	v_mov_b32_e32 v123, v147
	v_pk_add_f32 v[114:115], v[122:123], v[114:115]
	v_mov_b32_e32 v89, v146
	v_pk_add_f32 v[88:89], v[88:89], v[114:115]
	v_rcp_f32_e32 v108, v108
	v_mul_f32_e32 v114, 0xbfb8aa3b, v89
	v_exp_f32_e32 v114, v114
	v_mul_f32_e32 v115, 0xbfb8aa3b, v88
	v_exp_f32_e32 v122, v115
	v_mov_b32_e32 v124, v120
	v_add_f32_e32 v114, 1.0, v114
	v_rcp_f32_e32 v115, v114
	v_add_f32_e32 v114, 1.0, v122
	v_rcp_f32_e32 v114, v114
	v_mov_b32_e32 v125, v162
	v_mov_b32_e32 v162, v121
	v_pk_add_f32 v[120:121], v[124:125], v[162:163]
	v_mov_b32_e32 v124, v137
	v_mov_b32_e32 v125, v127
	v_pk_mul_f32 v[122:123], v[116:117], v[116:117]
	v_pk_add_f32 v[120:121], v[124:125], v[120:121]
	v_mov_b32_e32 v137, v126
	v_pk_mul_f32 v[106:107], v[106:107], v[108:109]
	v_pk_mul_f32 v[88:89], v[88:89], v[114:115]
	v_pk_add_f32 v[120:121], v[136:137], v[120:121]
	v_mov_b32_e32 v124, v123
	v_mov_b32_e32 v125, v139
	v_pk_mul_f32 v[108:109], v[106:107], v[106:107]
	v_pk_mul_f32 v[114:115], v[88:89], v[88:89]
	v_pk_add_f32 v[120:121], v[124:125], v[120:121]
	v_mov_b32_e32 v123, v138
	v_pk_add_f32 v[120:121], v[122:123], v[120:121]
	v_mov_b32_e32 v122, v115
	v_mov_b32_e32 v123, v109
	v_pk_add_f32 v[120:121], v[122:123], v[120:121]
	v_mov_b32_e32 v115, v108
	v_pk_add_f32 v[108:109], v[114:115], v[120:121]
	ds_bpermute_b32 v115, v197, v109
	ds_bpermute_b32 v114, v197, v108
	v_mul_f32_e32 v120, 0xbfb8aa3b, v208
	v_mul_f32_e32 v121, 0xbfb8aa3b, v205
	v_exp_f32_e32 v120, v120
	v_exp_f32_e32 v121, v121
	s_waitcnt lgkmcnt(0)
	v_pk_add_f32 v[108:109], v[108:109], v[114:115]
	ds_bpermute_b32 v115, v196, v109
	ds_bpermute_b32 v114, v196, v108
	v_add_f32_e32 v120, 1.0, v120
	v_add_f32_e32 v121, 1.0, v121
	v_rcp_f32_e32 v120, v120
	v_rcp_f32_e32 v121, v121
	s_waitcnt lgkmcnt(0)
	v_pk_add_f32 v[108:109], v[108:109], v[114:115]
	ds_bpermute_b32 v115, v195, v109
	ds_bpermute_b32 v114, v195, v108
	v_mul_f32_e32 v122, v211, v207
	v_mul_f32_e32 v123, v204, v168
	v_mul_f32_e32 v120, v208, v120
	v_mul_f32_e32 v121, v205, v121
	s_waitcnt lgkmcnt(0)
; #define LAS __attribute__((address_space(3)))
; __device__ __forceinline__ bf16_t f2bf(float f) { return (bf16_t)(pk2(f, 0.f) & 0xffffu); }
; __device__ __forceinline__ float fexp(float x) { return __expf(x); }
; __device__ __forceinline__ void gdn_unit(const Ctx& X, LAS unsigned char* hl, int b, int c, int h, int tid_h, int w4, int lane, int layer) {
;     ...
;         for (int rs = 0; rs < 2; ++rs) {
;             const int i = i0 + 32 * rs;
;             const float bi = Bs[i], Gi = Gs[i];
;             float y[3][8];
; #pragma unroll
;             for (int tn = 0; tn < 3; ++tn) {
; #pragma unroll
;                 for (int e = 0; e < 8; ++e) y[tn][e] = 0.f;
; #pragma unroll
;                 for (int k = 0; k < 4; ++k) { float x8[8]; unpack8(*(const LAS u32x4*)(RAW + (tn * 67 + i + k) * 64 + cseg * 8), x8);
;                     y[tn][0] += wq[tn][k][0].x * x8[0]; y[tn][1] += wq[tn][k][0].y * x8[1]; y[tn][2] += wq[tn][k][0].z * x8[2]; y[tn][3] += wq[tn][k][0].w * x8[3];
;                     y[tn][4] += wq[tn][k][1].x * x8[4]; y[tn][5] += wq[tn][k][1].y * x8[5]; y[tn][6] += wq[tn][k][1].z * x8[6]; y[tn][7] += wq[tn][k][1].w * x8[7]; }
;     ...
;             float sq = 0.f, sk = 0.f;
; #pragma unroll
;             for (int e = 0; e < 8; ++e) { sq += y[0][e] * y[0][e]; sk += y[1][e] * y[1][e]; }
;             sq += __shfl_xor(sq, 1); sq += __shfl_xor(sq, 2); sq += __shfl_xor(sq, 4);
;             sk += __shfl_xor(sk, 1); sk += __shfl_xor(sk, 2); sk += __shfl_xor(sk, 4);
;             const float rq = 0.125f * rsqrtf(sq + 1e-6f), rk = rsqrtf(sk + 1e-6f), kd = rk * fexp(G63 - Gi);
;             float t8[8];
; #pragma unroll
;             for (int e = 0; e < 8; ++e) t8[e] = y[0][e] * rq;
;             *(LAS u32x4*)(Q + i * LT + cseg * 8) = pack8(t8);
; #pragma unroll
;             for (int e = 0; e < 8; ++e) t8[e] = y[1][e] * rk;
;             *(LAS u32x4*)(K + i * LT + cseg * 8) = pack8(t8);
; #pragma unroll
;             for (int e = 0; e < 8; ++e) t8[e] = y[1][e] * rk * bi;
;             *(LAS u32x4*)(KB + i * LT + cseg * 8) = pack8(t8);
;             *(LAS u32x4*)(V + i * LT + cseg * 8) = pack8(y[2]);
; #pragma unroll
;             for (int e = 0; e < 8; ++e) KDT[(cseg * 8 + e) * LT + i] = f2bf(y[1][e] * kd);
	v_pk_add_f32 v[108:109], v[108:109], v[114:115]
	v_sub_f32_e32 v115, v194, v201
	v_pk_add_f32 v[108:109], v[108:109], s[4:5] op_sel_hi:[1,0]
	v_mul_f32_e32 v115, 0x3fb8aa3b, v115
	v_mul_f32_e32 v114, 0x4b800000, v109
	v_cmp_gt_f32_e32 vcc, s3, v109
	v_cmp_gt_f32_e64 s[0:1], s3, v108
	v_exp_f32_e32 v124, v115
	v_cndmask_b32_e32 v109, v109, v114, vcc
	v_rsq_f32_e32 v109, v109
	v_mul_f32_e32 v114, 0x4b800000, v108
	v_cndmask_b32_e64 v108, v108, v114, s[0:1]
	v_rsq_f32_e32 v108, v108
	v_mul_f32_e32 v114, 0x45800000, v109
	v_cndmask_b32_e32 v109, v109, v114, vcc
	v_mul_f32_e32 v109, 0x3e000000, v109
	v_mul_f32_e32 v114, 0x45800000, v108
	v_mul_f32_e32 v115, v134, v109
	v_mul_f32_e32 v125, v135, v109
	v_mul_f32_e32 v119, v119, v109
	v_mul_f32_e32 v118, v118, v109
	v_mul_f32_e32 v126, v113, v109
	v_mul_f32_e32 v127, v112, v109
	v_mul_f32_e32 v107, v107, v109
	v_mul_f32_e32 v106, v106, v109
	v_cndmask_b32_e64 v109, v108, v114, s[0:1]
	v_mul_lo_u32 v108, v191, s44
	v_cvt_pk_bf16_f32 v112, v115, v125
	v_cvt_pk_bf16_f32 v113, v119, v118
	v_cvt_pk_bf16_f32 v114, v126, v127
	v_cvt_pk_bf16_f32 v115, v107, v106
	v_add_u32_e32 v106, v193, v108
	ds_write_b128 v106, v[112:115]
	v_mul_f32_e32 v106, v80, v109
	v_mul_f32_e32 v107, v81, v109
	v_mul_f32_e32 v118, v111, v109
	v_mul_f32_e32 v119, v110, v109
	v_mul_f32_e32 v125, v117, v109
	v_mul_f32_e32 v126, v116, v109
	v_mul_f32_e32 v127, v89, v109
	v_mul_f32_e32 v128, v88, v109
	v_cvt_pk_bf16_f32 v112, v106, v107
	v_cvt_pk_bf16_f32 v113, v118, v119
	v_cvt_pk_bf16_f32 v114, v125, v126
	v_cvt_pk_bf16_f32 v115, v127, v128
	v_add_u32_e32 v129, v192, v108
	v_mul_f32_e32 v106, v200, v106
	ds_write_b128 v129, v[112:115]
	v_mul_f32_e32 v107, v200, v107
	v_mul_f32_e32 v113, v200, v118
	v_mul_f32_e32 v114, v200, v119
	v_mul_f32_e32 v115, v200, v125
	v_cvt_pk_bf16_f32 v112, v106, v107
	v_add_u32_e32 v106, v155, v108
	v_mul_f32_e32 v118, v200, v126
	v_mul_f32_e32 v119, v200, v127
	v_mul_f32_e32 v125, v200, v128
	v_mul_f32_e32 v109, v124, v109
	v_cvt_pk_bf16_f32 v113, v113, v114
	v_cvt_pk_bf16_f32 v114, v115, v118
	v_cvt_pk_bf16_f32 v115, v119, v125
	ds_write_b128 v106, v[112:115]
	v_add_u32_e32 v106, v133, v108
	v_cvt_pk_bf16_f32 v112, v202, v206
	v_cvt_pk_bf16_f32 v113, v210, v203
	v_cvt_pk_bf16_f32 v114, v122, v123
	v_cvt_pk_bf16_f32 v115, v120, v121
	ds_write_b128 v106, v[112:115]
	v_lshlrev_b32_e32 v106, 1, v191
	v_mul_f32_e32 v80, v80, v109
	v_mul_u32_u24_e32 v107, 0x90, v190
	v_cvt_pk_bf16_f32 v80, v80, v157
	v_add3_u32 v107, v131, v106, v107
	ds_write_b16 v107, v80
	v_mul_f32_e32 v80, v81, v109
	v_cvt_pk_bf16_f32 v80, v80, v157
	ds_write_b16 v107, v80 offset:144
	v_mul_f32_e32 v80, v111, v109
	v_cvt_pk_bf16_f32 v80, v80, v157
	ds_write_b16 v107, v80 offset:288
	v_mul_f32_e32 v80, v110, v109
	v_cvt_pk_bf16_f32 v80, v80, v157
	ds_write_b16 v107, v80 offset:432
	v_mul_f32_e32 v80, v117, v109
	v_cvt_pk_bf16_f32 v80, v80, v157
	ds_write_b16 v107, v80 offset:576
	v_mul_f32_e32 v80, v116, v109
	v_cvt_pk_bf16_f32 v80, v80, v157
	ds_write_b16 v107, v80 offset:720
	v_mul_f32_e32 v80, v89, v109
	v_cvt_pk_bf16_f32 v80, v80, v157
	ds_write_b16 v107, v80 offset:864
	v_mul_f32_e32 v80, v88, v109
	v_cvt_pk_bf16_f32 v80, v80, v157
	ds_write_b16 v107, v80 offset:1008
	ds_read_b128 v[112:115], v156 offset:4224
	ds_read_b128 v[116:119], v156 offset:4096
	ds_read_b32 v109, v198 offset:128
	ds_read_b32 v110, v199 offset:128
	ds_read_b128 v[120:123], v156 offset:4352
	ds_read_b128 v[124:127], v156 offset:4480
	v_and_b32_e32 v106, 15, v130
	s_waitcnt lgkmcnt(5)
	v_lshlrev_b32_e32 v81, 16, v112
	s_waitcnt lgkmcnt(4)
	v_lshlrev_b32_e32 v80, 16, v116
	v_pk_mul_f32 v[88:89], v[102:103], v[80:81]
	v_and_b32_e32 v81, 0xffff0000, v112
	v_and_b32_e32 v80, 0xffff0000, v116
	v_pk_mul_f32 v[102:103], v[74:75], v[80:81]
	v_lshlrev_b32_e32 v75, 16, v117
	v_lshlrev_b32_e32 v74, 16, v113
	v_pk_mul_f32 v[74:75], v[66:67], v[74:75]
	v_and_b32_e32 v67, 0xffff0000, v117
	v_and_b32_e32 v66, 0xffff0000, v113
	v_pk_mul_f32 v[80:81], v[68:69], v[66:67]
	v_and_b32_e32 v69, 0xffff0000, v118
	v_and_b32_e32 v68, 0xffff0000, v114
	v_pk_mul_f32 v[68:69], v[58:59], v[68:69]
	v_lshlrev_b32_e32 v59, 16, v119
	v_lshlrev_b32_e32 v58, 16, v115
	v_pk_mul_f32 v[58:59], v[76:77], v[58:59]
	v_and_b32_e32 v77, 0xffff0000, v119
	v_and_b32_e32 v76, 0xffff0000, v115
	v_pk_mul_f32 v[60:61], v[60:61], v[76:77]
	s_waitcnt lgkmcnt(0)
	v_lshlrev_b32_e32 v77, 16, v124
	v_lshlrev_b32_e32 v76, 16, v120
	v_lshlrev_b32_e32 v67, 16, v114
	v_lshlrev_b32_e32 v66, 16, v118
	v_pk_mul_f32 v[98:99], v[98:99], v[76:77]
	v_and_b32_e32 v77, 0xffff0000, v124
	v_and_b32_e32 v76, 0xffff0000, v120
	v_pk_mul_f32 v[66:67], v[104:105], v[66:67]
	v_pk_mul_f32 v[104:105], v[70:71], v[76:77]
	v_lshlrev_b32_e32 v71, 16, v121
	v_lshlrev_b32_e32 v70, 16, v125
	ds_read_b128 v[112:115], v156 offset:12672
	ds_read_b128 v[116:119], v156 offset:12800
	v_pk_mul_f32 v[70:71], v[62:63], v[70:71]
	v_and_b32_e32 v63, 0xffff0000, v121
	v_and_b32_e32 v62, 0xffff0000, v125
	v_pk_mul_f32 v[76:77], v[64:65], v[62:63]
	v_and_b32_e32 v65, 0xffff0000, v122
	v_and_b32_e32 v64, 0xffff0000, v126
	v_pk_mul_f32 v[64:65], v[54:55], v[64:65]
	v_lshlrev_b32_e32 v55, 16, v123
	v_lshlrev_b32_e32 v54, 16, v127
	v_pk_mul_f32 v[54:55], v[72:73], v[54:55]
	v_and_b32_e32 v73, 0xffff0000, v123
	v_and_b32_e32 v72, 0xffff0000, v127
	v_pk_mul_f32 v[56:57], v[56:57], v[72:73]
	s_waitcnt lgkmcnt(0)
; #define LAS __attribute__((address_space(3)))
; __device__ __forceinline__ float silu_acc(float x) { return x * frcp(1.0f + fexp(-x)); }
; __device__ __forceinline__ void gdn_unit(const Ctx& X, LAS unsigned char* hl, int b, int c, int h, int tid_h, int w4, int lane, int layer) {
;     ...
;             for (int tn = 0; tn < 3; ++tn) {
; #pragma unroll
;                 for (int e = 0; e < 8; ++e) y[tn][e] = 0.f;
; #pragma unroll
;                 for (int k = 0; k < 4; ++k) { float x8[8]; unpack8(*(const LAS u32x4*)(RAW + (tn * 67 + i + k) * 64 + cseg * 8), x8);
;                     y[tn][0] += wq[tn][k][0].x * x8[0]; y[tn][1] += wq[tn][k][0].y * x8[1]; y[tn][2] += wq[tn][k][0].z * x8[2]; y[tn][3] += wq[tn][k][0].w * x8[3];
;                     y[tn][4] += wq[tn][k][1].x * x8[4]; y[tn][5] += wq[tn][k][1].y * x8[5]; y[tn][6] += wq[tn][k][1].z * x8[6]; y[tn][7] += wq[tn][k][1].w * x8[7]; }
; #pragma unroll
;                 for (int e = 0; e < 8; ++e) y[tn][e] = silu_acc(y[tn][e]);
;             }
	v_lshlrev_b32_e32 v73, 16, v116
	v_lshlrev_b32_e32 v72, 16, v112
	v_lshlrev_b32_e32 v63, 16, v126
	v_lshlrev_b32_e32 v62, 16, v122
	v_pk_mul_f32 v[94:95], v[94:95], v[72:73]
	v_and_b32_e32 v73, 0xffff0000, v116
	v_and_b32_e32 v72, 0xffff0000, v112
	v_pk_mul_f32 v[62:63], v[100:101], v[62:63]
	v_pk_mul_f32 v[100:101], v[50:51], v[72:73]
	v_lshlrev_b32_e32 v51, 16, v113
	v_lshlrev_b32_e32 v50, 16, v117
	ds_read_b128 v[120:123], v156 offset:12928
	ds_read_b128 v[124:127], v156 offset:13056
	v_pk_mul_f32 v[50:51], v[46:47], v[50:51]
	v_and_b32_e32 v47, 0xffff0000, v113
	v_and_b32_e32 v46, 0xffff0000, v117
	v_pk_mul_f32 v[72:73], v[48:49], v[46:47]
	v_and_b32_e32 v49, 0xffff0000, v114
	v_and_b32_e32 v48, 0xffff0000, v118
	v_pk_mul_f32 v[48:49], v[38:39], v[48:49]
	v_lshlrev_b32_e32 v39, 16, v115
	v_lshlrev_b32_e32 v38, 16, v119
	v_pk_mul_f32 v[38:39], v[52:53], v[38:39]
	v_and_b32_e32 v53, 0xffff0000, v115
	v_and_b32_e32 v52, 0xffff0000, v119
	v_pk_mul_f32 v[40:41], v[40:41], v[52:53]
	s_waitcnt lgkmcnt(0)
	v_lshlrev_b32_e32 v53, 16, v124
	v_lshlrev_b32_e32 v52, 16, v120
	v_lshlrev_b32_e32 v47, 16, v118
	v_lshlrev_b32_e32 v46, 16, v114
	v_pk_mul_f32 v[90:91], v[90:91], v[52:53]
	v_and_b32_e32 v53, 0xffff0000, v124
	v_and_b32_e32 v52, 0xffff0000, v120
	v_pk_mul_f32 v[46:47], v[96:97], v[46:47]
	v_pk_mul_f32 v[96:97], v[42:43], v[52:53]
	v_lshlrev_b32_e32 v43, 16, v121
	v_lshlrev_b32_e32 v42, 16, v125
	ds_read_b128 v[112:115], v156 offset:21248
	ds_read_b128 v[116:119], v156 offset:21376
	v_pk_mul_f32 v[42:43], v[34:35], v[42:43]
	v_and_b32_e32 v35, 0xffff0000, v121
	v_and_b32_e32 v34, 0xffff0000, v125
	v_pk_mul_f32 v[52:53], v[36:37], v[34:35]
	v_and_b32_e32 v37, 0xffff0000, v122
	v_and_b32_e32 v36, 0xffff0000, v126
	v_pk_mul_f32 v[36:37], v[30:31], v[36:37]
	v_lshlrev_b32_e32 v31, 16, v123
	v_lshlrev_b32_e32 v30, 16, v127
	v_pk_mul_f32 v[30:31], v[44:45], v[30:31]
	v_and_b32_e32 v45, 0xffff0000, v123
	v_and_b32_e32 v44, 0xffff0000, v127
	v_pk_mul_f32 v[32:33], v[32:33], v[44:45]
	s_waitcnt lgkmcnt(0)
	v_lshlrev_b32_e32 v45, 16, v116
	v_lshlrev_b32_e32 v44, 16, v112
	v_pk_mul_f32 v[44:45], v[86:87], v[44:45]
	v_lshlrev_b32_e32 v35, 16, v126
	v_add_f32_e32 v44, 0, v44
	v_add_f32_e32 v86, v44, v45
	v_and_b32_e32 v45, 0xffff0000, v116
	v_and_b32_e32 v44, 0xffff0000, v112
	v_pk_mul_f32 v[26:27], v[26:27], v[44:45]
	v_lshlrev_b32_e32 v34, 16, v122
	v_add_f32_e32 v26, 0, v26
	v_add_f32_e32 v44, v26, v27
	v_lshlrev_b32_e32 v27, 16, v113
	v_lshlrev_b32_e32 v26, 16, v117
	v_pk_mul_f32 v[22:23], v[22:23], v[26:27]
	v_pk_mul_f32 v[34:35], v[92:93], v[34:35]
	v_add_f32_e32 v23, 0, v23
	v_add_f32_e32 v45, v22, v23
	v_and_b32_e32 v23, 0xffff0000, v113
	v_and_b32_e32 v22, 0xffff0000, v117
	v_pk_mul_f32 v[22:23], v[24:25], v[22:23]
	s_nop 0
	v_add_f32_e32 v23, 0, v23
	v_add_f32_e32 v87, v22, v23
	v_lshlrev_b32_e32 v23, 16, v118
	v_lshlrev_b32_e32 v22, 16, v114
	v_pk_mul_f32 v[22:23], v[28:29], v[22:23]
	s_nop 0
	v_add_f32_e32 v22, 0, v22
	v_add_f32_e32 v92, v22, v23
	v_and_b32_e32 v23, 0xffff0000, v114
	v_and_b32_e32 v22, 0xffff0000, v118
	v_pk_mul_f32 v[14:15], v[14:15], v[22:23]
	ds_read_b128 v[22:25], v156 offset:21504
	ds_read_b128 v[26:29], v156 offset:21632
	v_add_f32_e32 v15, 0, v15
	v_add_f32_e32 v93, v14, v15
	v_lshlrev_b32_e32 v15, 16, v115
	v_lshlrev_b32_e32 v14, 16, v119
	v_pk_mul_f32 v[14:15], v[82:83], v[14:15]
	s_nop 0
	v_add_f32_e32 v15, 0, v15
	v_add_f32_e32 v82, v14, v15
	v_and_b32_e32 v15, 0xffff0000, v115
	v_and_b32_e32 v14, 0xffff0000, v119
	v_pk_mul_f32 v[14:15], v[16:17], v[14:15]
	s_nop 0
	v_add_f32_e32 v15, 0, v15
	v_add_f32_e32 v16, v14, v15
	s_waitcnt lgkmcnt(0)
	v_lshlrev_b32_e32 v15, 16, v26
	v_lshlrev_b32_e32 v14, 16, v22
	v_pk_mul_f32 v[14:15], v[84:85], v[14:15]
	s_nop 0
	v_add_f32_e32 v14, v86, v14
	v_add_f32_e32 v17, v14, v15
	v_and_b32_e32 v15, 0xffff0000, v26
	v_and_b32_e32 v14, 0xffff0000, v22
	v_pk_mul_f32 v[14:15], v[18:19], v[14:15]
	v_mov_b32_e32 v19, v51
	v_add_f32_e32 v14, v44, v14
	v_add_f32_e32 v18, v14, v15
	v_lshlrev_b32_e32 v15, 16, v23
	v_lshlrev_b32_e32 v14, 16, v27
	v_pk_mul_f32 v[10:11], v[10:11], v[14:15]
	s_nop 0
	v_add_f32_e32 v11, v11, v45
	v_add_f32_e32 v14, v10, v11
	v_and_b32_e32 v11, 0xffff0000, v23
	v_and_b32_e32 v10, 0xffff0000, v27
	v_pk_mul_f32 v[10:11], v[12:13], v[10:11]
	v_mov_b32_e32 v13, v96
	v_add_f32_e32 v11, v11, v87
	v_add_f32_e32 v12, v10, v11
	v_lshlrev_b32_e32 v11, 16, v28
	v_lshlrev_b32_e32 v10, 16, v24
	v_pk_mul_f32 v[10:11], v[20:21], v[10:11]
	v_mov_b32_e32 v96, v91
	v_add_f32_e32 v10, v92, v10
	v_add_f32_e32 v44, v10, v11
	v_and_b32_e32 v11, 0xffff0000, v24
	v_and_b32_e32 v10, 0xffff0000, v28
	v_pk_mul_f32 v[6:7], v[6:7], v[10:11]
	v_mov_b32_e32 v11, v100
	v_add_f32_e32 v7, v7, v93
	v_add_f32_e32 v45, v6, v7
	v_lshlrev_b32_e32 v7, 16, v25
	v_lshlrev_b32_e32 v6, 16, v29
	v_pk_mul_f32 v[6:7], v[78:79], v[6:7]
	v_mov_b32_e32 v100, v95
	v_add_f32_e32 v7, v7, v82
	v_add_f32_e32 v78, v6, v7
	v_mul_f32_e32 v6, 0xbfb8aa3b, v17
	v_exp_f32_e32 v10, v6
	v_and_b32_e32 v7, 0xffff0000, v25
	v_and_b32_e32 v6, 0xffff0000, v29
	v_pk_mul_f32 v[6:7], v[8:9], v[6:7]
	v_mul_f32_e32 v9, 0xbfb8aa3b, v18
	v_exp_f32_e32 v9, v9
	v_add_f32_e32 v8, 1.0, v10
	v_rcp_f32_e32 v8, v8
	v_add_f32_e32 v7, v7, v16
	v_add_f32_e32 v79, v6, v7
	v_add_f32_e32 v6, 1.0, v9
	v_mul_f32_e32 v9, 0xbfb8aa3b, v44
	v_mul_f32_e32 v7, 0xbfb8aa3b, v14
	v_rcp_f32_e32 v6, v6
	v_exp_f32_e32 v9, v9
	v_exp_f32_e32 v7, v7
	v_mul_f32_e32 v82, v17, v8
	v_mul_f32_e32 v8, 0xbfb8aa3b, v12
	v_exp_f32_e32 v8, v8
	v_mul_f32_e32 v83, v18, v6
	v_add_f32_e32 v6, 1.0, v9
	v_add_f32_e32 v7, 1.0, v7
	v_rcp_f32_e32 v86, v6
	v_mul_f32_e32 v6, 0xbfb8aa3b, v45
; __device__ __forceinline__ float silu_acc(float x) { return x * frcp(1.0f + fexp(-x)); }
; __device__ __forceinline__ void gdn_unit(const Ctx& X, LAS unsigned char* hl, int b, int c, int h, int tid_h, int w4, int lane, int layer) {
;     ...
;                 for (int e = 0; e < 8; ++e) y[tn][e] = silu_acc(y[tn][e]);
;             }
;             float sq = 0.f, sk = 0.f;
; #pragma unroll
;             for (int e = 0; e < 8; ++e) { sq += y[0][e] * y[0][e]; sk += y[1][e] * y[1][e]; }
;             sq += __shfl_xor(sq, 1); sq += __shfl_xor(sq, 2); sq += __shfl_xor(sq, 4);
;             sk += __shfl_xor(sk, 1); sk += __shfl_xor(sk, 2); sk += __shfl_xor(sk, 4);
	v_rcp_f32_e32 v7, v7
	v_exp_f32_e32 v10, v6
	v_add_f32_e32 v8, 1.0, v8
	v_rcp_f32_e32 v8, v8
	v_mul_f32_e32 v84, v14, v7
	v_mov_b32_e32 v6, v88
	v_mov_b32_e32 v7, v102
	v_add_f32_e32 v14, 1.0, v10
	v_mov_b32_e32 v10, v94
	v_pk_add_f32 v[6:7], v[6:7], 0 op_sel_hi:[1,0]
	v_mov_b32_e32 v102, v89
	v_pk_add_f32 v[10:11], v[10:11], 0 op_sel_hi:[1,0]
	v_mul_f32_e32 v85, v12, v8
	v_pk_add_f32 v[6:7], v[6:7], v[102:103]
	v_mov_b32_e32 v8, v98
	v_mov_b32_e32 v9, v104
	v_pk_add_f32 v[10:11], v[10:11], v[100:101]
	v_mov_b32_e32 v12, v90
	v_pk_add_f32 v[6:7], v[6:7], v[8:9]
	v_mov_b32_e32 v104, v99
	v_pk_add_f32 v[10:11], v[10:11], v[12:13]
	v_pk_add_f32 v[6:7], v[6:7], v[104:105]
	v_pk_add_f32 v[10:11], v[10:11], v[96:97]
	v_mul_f32_e32 v8, 0xbfb8aa3b, v6
	v_mul_f32_e32 v9, 0xbfb8aa3b, v7
	v_mul_f32_e32 v12, 0xbfb8aa3b, v10
	v_mul_f32_e32 v13, 0xbfb8aa3b, v11
	v_exp_f32_e32 v8, v8
	v_exp_f32_e32 v9, v9
	v_exp_f32_e32 v12, v12
	v_exp_f32_e32 v13, v13
	v_add_f32_e32 v8, 1.0, v8
	v_add_f32_e32 v9, 1.0, v9
	v_add_f32_e32 v12, 1.0, v12
	v_add_f32_e32 v13, 1.0, v13
	v_rcp_f32_e32 v8, v8
	v_rcp_f32_e32 v9, v9
	v_rcp_f32_e32 v12, v12
	v_rcp_f32_e32 v13, v13
	v_mov_b32_e32 v20, v53
	v_pk_mul_f32 v[8:9], v[6:7], v[8:9]
	v_mov_b32_e32 v21, v43
	v_pk_mul_f32 v[6:7], v[10:11], v[12:13]
	v_mov_b32_e32 v10, v81
	v_mov_b32_e32 v11, v75
	v_pk_add_f32 v[10:11], v[10:11], 0 op_sel_hi:[1,0]
	v_mov_b32_e32 v81, v74
	v_pk_add_f32 v[10:11], v[80:81], v[10:11]
	v_mov_b32_e32 v12, v77
	v_mov_b32_e32 v13, v71
	v_pk_add_f32 v[10:11], v[12:13], v[10:11]
	v_mov_b32_e32 v77, v70
	v_pk_add_f32 v[10:11], v[76:77], v[10:11]
	v_mov_b32_e32 v53, v42
	v_mul_f32_e32 v12, 0xbfb8aa3b, v11
	v_exp_f32_e32 v16, v12
	v_mul_f32_e32 v12, 0xbfb8aa3b, v10
	v_exp_f32_e32 v18, v12
	v_pk_mov_b32 v[22:23], v[64:65], v[62:63] op_sel:[1,0]
	v_add_f32_e32 v16, 1.0, v16
	v_rcp_f32_e32 v17, v16
	v_add_f32_e32 v16, 1.0, v18
	v_mov_b32_e32 v18, v73
	v_pk_add_f32 v[18:19], v[18:19], 0 op_sel_hi:[1,0]
	v_mov_b32_e32 v73, v50
	v_pk_add_f32 v[18:19], v[72:73], v[18:19]
	v_rcp_f32_e32 v16, v16
	v_pk_add_f32 v[18:19], v[20:21], v[18:19]
	v_mov_b32_e32 v65, v63
	v_pk_add_f32 v[18:19], v[52:53], v[18:19]
	v_pk_mul_f32 v[10:11], v[10:11], v[16:17]
	v_mul_f32_e32 v20, 0xbfb8aa3b, v19
	v_exp_f32_e32 v20, v20
	v_mul_f32_e32 v21, 0xbfb8aa3b, v18
	v_exp_f32_e32 v21, v21
	v_pk_mov_b32 v[26:27], v[36:37], v[34:35] op_sel:[1,0]
	v_add_f32_e32 v16, 1.0, v20
	v_rcp_f32_e32 v17, v16
	v_add_f32_e32 v16, 1.0, v21
	v_pk_mov_b32 v[20:21], v[68:69], v[66:67] op_sel:[1,0]
	v_mov_b32_e32 v69, v67
	v_pk_add_f32 v[20:21], v[20:21], 0 op_sel_hi:[1,0]
	v_mov_b32_e32 v37, v35
	v_pk_add_f32 v[20:21], v[68:69], v[20:21]
	v_mov_b32_e32 v35, v59
	v_pk_add_f32 v[20:21], v[22:23], v[20:21]
	v_rcp_f32_e32 v16, v16
	v_pk_add_f32 v[20:21], v[64:65], v[20:21]
	v_rcp_f32_e32 v87, v14
	v_mul_f32_e32 v22, 0xbfb8aa3b, v21
	v_exp_f32_e32 v22, v22
	v_mul_f32_e32 v23, 0xbfb8aa3b, v20
	v_exp_f32_e32 v24, v23
	v_pk_mul_f32 v[14:15], v[8:9], v[8:9]
	v_add_f32_e32 v22, 1.0, v22
	v_rcp_f32_e32 v23, v22
	v_add_f32_e32 v22, 1.0, v24
	v_rcp_f32_e32 v22, v22
	v_pk_mul_f32 v[12:13], v[6:7], v[6:7]
	v_pk_mul_f32 v[16:17], v[18:19], v[16:17]
	v_pk_mul_f32 v[24:25], v[10:11], v[10:11]
	v_pk_mul_f32 v[20:21], v[20:21], v[22:23]
	v_pk_mov_b32 v[22:23], v[48:49], v[46:47] op_sel:[1,0]
	v_mov_b32_e32 v49, v47
	v_pk_add_f32 v[22:23], v[22:23], 0 op_sel_hi:[1,0]
	v_pk_mul_f32 v[18:19], v[16:17], v[16:17]
	v_pk_add_f32 v[22:23], v[48:49], v[22:23]
	v_ashrrev_i32_e32 v72, 4, v130
	v_pk_add_f32 v[22:23], v[26:27], v[22:23]
	v_lshlrev_b32_e32 v77, 2, v72
	v_pk_add_f32 v[22:23], v[36:37], v[22:23]
	v_mov_b32_e32 v36, v57
	v_mul_f32_e32 v26, 0xbfb8aa3b, v23
	v_exp_f32_e32 v28, v26
	v_mul_f32_e32 v26, 0xbfb8aa3b, v22
	v_exp_f32_e32 v34, v26
	v_mov_b32_e32 v37, v55
	v_add_f32_e32 v28, 1.0, v28
	v_rcp_f32_e32 v29, v28
	v_add_f32_e32 v28, 1.0, v34
	v_mov_b32_e32 v34, v61
	v_pk_add_f32 v[34:35], v[34:35], 0 op_sel_hi:[1,0]
	v_mov_b32_e32 v61, v58
	v_pk_add_f32 v[34:35], v[60:61], v[34:35]
	v_mov_b32_e32 v57, v54
	v_pk_add_f32 v[34:35], v[36:37], v[34:35]
	v_rcp_f32_e32 v28, v28
	v_pk_add_f32 v[34:35], v[56:57], v[34:35]
	v_pk_mul_f32 v[26:27], v[20:21], v[20:21]
	v_mul_f32_e32 v36, 0xbfb8aa3b, v35
	v_exp_f32_e32 v36, v36
	v_mul_f32_e32 v37, 0xbfb8aa3b, v34
	v_exp_f32_e32 v37, v37
	v_pk_mul_f32 v[22:23], v[22:23], v[28:29]
	v_add_f32_e32 v28, 1.0, v36
	v_rcp_f32_e32 v29, v28
	v_add_f32_e32 v28, 1.0, v37
	v_mov_b32_e32 v36, v41
	v_mov_b32_e32 v37, v39
	v_pk_add_f32 v[36:37], v[36:37], 0 op_sel_hi:[1,0]
	v_mov_b32_e32 v41, v38
	v_pk_add_f32 v[36:37], v[40:41], v[36:37]
	v_mov_b32_e32 v38, v33
	v_mov_b32_e32 v39, v31
	v_pk_add_f32 v[36:37], v[38:39], v[36:37]
	v_mov_b32_e32 v33, v30
	v_pk_add_f32 v[30:31], v[32:33], v[36:37]
	v_rcp_f32_e32 v28, v28
	v_mul_f32_e32 v32, 0xbfb8aa3b, v31
	v_exp_f32_e32 v32, v32
	v_mul_f32_e32 v33, 0xbfb8aa3b, v30
	v_exp_f32_e32 v36, v33
	v_mov_b32_e32 v38, v12
	v_add_f32_e32 v32, 1.0, v32
	v_rcp_f32_e32 v33, v32
	v_add_f32_e32 v32, 1.0, v36
	v_rcp_f32_e32 v32, v32
	v_mov_b32_e32 v39, v14
	v_mov_b32_e32 v14, v13
	v_pk_add_f32 v[12:13], v[38:39], v[14:15]
	v_mov_b32_e32 v14, v19
	v_mov_b32_e32 v15, v25
	v_pk_mul_f32 v[36:37], v[22:23], v[22:23]
	v_pk_add_f32 v[12:13], v[14:15], v[12:13]
	v_mov_b32_e32 v19, v24
	v_pk_mul_f32 v[28:29], v[34:35], v[28:29]
	v_pk_mul_f32 v[30:31], v[30:31], v[32:33]
	v_pk_add_f32 v[12:13], v[18:19], v[12:13]
	v_mov_b32_e32 v14, v37
	v_mov_b32_e32 v15, v27
	v_pk_mul_f32 v[34:35], v[28:29], v[28:29]
	v_pk_mul_f32 v[32:33], v[30:31], v[30:31]
	v_pk_add_f32 v[12:13], v[14:15], v[12:13]
	v_mov_b32_e32 v37, v26
	v_pk_add_f32 v[12:13], v[36:37], v[12:13]
	v_mov_b32_e32 v14, v33
	v_mov_b32_e32 v15, v35
	v_pk_add_f32 v[12:13], v[14:15], v[12:13]
	v_mov_b32_e32 v33, v34
	v_pk_add_f32 v[12:13], v[32:33], v[12:13]
	ds_bpermute_b32 v15, v197, v13
	ds_bpermute_b32 v14, v197, v12
	v_mul_f32_e32 v18, 0xbfb8aa3b, v78
	v_mul_f32_e32 v19, 0xbfb8aa3b, v79
	v_exp_f32_e32 v18, v18
	v_exp_f32_e32 v19, v19
	s_waitcnt lgkmcnt(0)
; #define LAS __attribute__((address_space(3)))
; __device__ __forceinline__ bf16_t f2bf(float f) { return (bf16_t)(pk2(f, 0.f) & 0xffffu); }
; __device__ __forceinline__ float fexp(float x) { return __expf(x); }
; __device__ __forceinline__ u32x4 pack8(const float (&f)[8]) { u32x4 w; w.x = pk2(f[0], f[1]); w.y = pk2(f[2], f[3]); w.z = pk2(f[4], f[5]); w.w = pk2(f[6], f[7]); return w; }
; #define LBAR() do { asm volatile("s_waitcnt lgkmcnt(0)" ::: "memory"); __builtin_amdgcn_s_barrier(); asm volatile("" ::: "memory"); } while (0)
; __device__ __forceinline__ void gdn_unit(const Ctx& X, LAS unsigned char* hl, int b, int c, int h, int tid_h, int w4, int lane, int layer) {
;     ...
;             const float rq = 0.125f * rsqrtf(sq + 1e-6f), rk = rsqrtf(sk + 1e-6f), kd = rk * fexp(G63 - Gi);
;             float t8[8];
; #pragma unroll
;             for (int e = 0; e < 8; ++e) t8[e] = y[0][e] * rq;
;             *(LAS u32x4*)(Q + i * LT + cseg * 8) = pack8(t8);
; #pragma unroll
;             for (int e = 0; e < 8; ++e) t8[e] = y[1][e] * rk;
;             *(LAS u32x4*)(K + i * LT + cseg * 8) = pack8(t8);
; #pragma unroll
;             for (int e = 0; e < 8; ++e) t8[e] = y[1][e] * rk * bi;
;             *(LAS u32x4*)(KB + i * LT + cseg * 8) = pack8(t8);
;             *(LAS u32x4*)(V + i * LT + cseg * 8) = pack8(y[2]);
; #pragma unroll
;             for (int e = 0; e < 8; ++e) KDT[(cseg * 8 + e) * LT + i] = f2bf(y[1][e] * kd);
;         }
;     }
;     LBAR();
;     }
;     {
;         f32x4 aA[4], aP[4];
; #pragma unroll
;         for (int ct = 0; ct < 4; ++ct) { aA[ct] = mma16(KB, 16 * w4, K, 16 * ct, (f32x4){0.f, 0.f, 0.f, 0.f}, r, q); aP[ct] = mma16(Q, 16 * w4, K, 16 * ct, (f32x4){0.f, 0.f, 0.f, 0.f}, r, q); }
; #pragma unroll
;         for (int ct = 0; ct < 4; ++ct)
; #pragma unroll
;             for (int j = 0; j < 4; ++j) { const int ii = 16 * w4 + 4 * q + j, col = 16 * ct + r;
;                 const float L = fexp(fminf(Gs[ii] - Gs[col], 0.f));
;                 AB[ii * LT + col] = f2bf(ii > col ? aA[ct][j] * L : 0.f);
;                 P[ii * LT + col] = f2bf(ii >= col ? aP[ct][j] * L : 0.f); }
;     }
	v_pk_add_f32 v[12:13], v[12:13], v[14:15]
	ds_bpermute_b32 v15, v196, v13
	ds_bpermute_b32 v14, v196, v12
	v_add_f32_e32 v18, 1.0, v18
	v_add_f32_e32 v19, 1.0, v19
	v_rcp_f32_e32 v18, v18
	v_rcp_f32_e32 v19, v19
	s_waitcnt lgkmcnt(0)
	v_pk_add_f32 v[12:13], v[12:13], v[14:15]
	ds_bpermute_b32 v15, v195, v13
	ds_bpermute_b32 v14, v195, v12
	v_mul_f32_e32 v24, v44, v86
	v_mul_f32_e32 v25, v45, v87
	v_mul_f32_e32 v18, v78, v18
	v_mul_f32_e32 v19, v79, v19
	s_waitcnt lgkmcnt(0)
	v_pk_add_f32 v[12:13], v[12:13], v[14:15]
	v_sub_f32_e32 v15, v194, v110
	v_pk_add_f32 v[12:13], v[12:13], s[4:5] op_sel_hi:[1,0]
	v_mul_f32_e32 v15, 0x3fb8aa3b, v15
	v_mul_f32_e32 v14, 0x4b800000, v13
	v_cmp_gt_f32_e32 vcc, s3, v13
	v_cmp_gt_f32_e64 s[0:1], s3, v12
	v_exp_f32_e32 v15, v15
	v_cndmask_b32_e32 v13, v13, v14, vcc
	v_rsq_f32_e32 v13, v13
	v_mul_f32_e32 v14, 0x4b800000, v12
	v_cndmask_b32_e64 v12, v12, v14, s[0:1]
	v_rsq_f32_e32 v12, v12
	v_mul_f32_e32 v14, 0x45800000, v13
	v_cndmask_b32_e32 v13, v13, v14, vcc
	v_mul_f32_e32 v13, 0x3e000000, v13
	v_mul_f32_e32 v8, v8, v13
	v_mul_f32_e32 v9, v9, v13
	v_mul_f32_e32 v11, v11, v13
	v_mul_f32_e32 v10, v10, v13
	v_mul_f32_e32 v21, v21, v13
	v_mul_f32_e32 v20, v20, v13
	v_mul_f32_e32 v26, v29, v13
	v_mul_f32_e32 v13, v28, v13
	v_mul_f32_e32 v14, 0x45800000, v12
	v_cvt_pk_bf16_f32 v8, v8, v9
	v_cvt_pk_bf16_f32 v9, v11, v10
	v_cvt_pk_bf16_f32 v10, v21, v20
	v_cvt_pk_bf16_f32 v11, v26, v13
	v_add_u32_e32 v13, 0x1200, v108
	v_cndmask_b32_e64 v12, v12, v14, s[0:1]
	v_add_u32_e32 v14, v193, v13
	ds_write_b128 v14, v[8:11]
	v_mul_f32_e32 v14, v6, v12
	v_mul_f32_e32 v20, v7, v12
	v_mul_f32_e32 v21, v17, v12
	v_mul_f32_e32 v26, v16, v12
	v_mul_f32_e32 v27, v23, v12
	v_mul_f32_e32 v28, v22, v12
	v_mul_f32_e32 v29, v31, v12
	v_mul_f32_e32 v32, v30, v12
	v_cvt_pk_bf16_f32 v8, v14, v20
	v_cvt_pk_bf16_f32 v9, v21, v26
	v_cvt_pk_bf16_f32 v10, v27, v28
	v_cvt_pk_bf16_f32 v11, v29, v32
	v_add_u32_e32 v33, v192, v13
	ds_write_b128 v33, v[8:11]
	v_mul_f32_e32 v8, v109, v14
	v_mul_f32_e32 v9, v109, v20
	v_mul_f32_e32 v10, v109, v21
	v_mul_f32_e32 v11, v109, v26
	v_mul_f32_e32 v14, v109, v27
	v_mul_f32_e32 v12, v15, v12
	v_mul_f32_e32 v20, v109, v28
	v_mul_f32_e32 v21, v109, v29
	v_mul_f32_e32 v26, v109, v32
	v_cvt_pk_bf16_f32 v8, v8, v9
	v_cvt_pk_bf16_f32 v9, v10, v11
	v_cvt_pk_bf16_f32 v10, v14, v20
	v_cvt_pk_bf16_f32 v11, v21, v26
	v_add_u32_e32 v14, v155, v13
	v_add_u32_e32 v13, v133, v13
	v_mul_f32_e32 v6, v6, v12
	ds_write_b128 v14, v[8:11]
	v_cvt_pk_bf16_f32 v8, v82, v83
	v_cvt_pk_bf16_f32 v9, v84, v85
	v_cvt_pk_bf16_f32 v10, v24, v25
	v_cvt_pk_bf16_f32 v11, v18, v19
	ds_write_b128 v13, v[8:11]
	v_cvt_pk_bf16_f32 v6, v6, v157
	ds_write_b16 v107, v6 offset:64
	v_mul_f32_e32 v6, v7, v12
	v_cvt_pk_bf16_f32 v6, v6, v157
	ds_write_b16 v107, v6 offset:208
	v_mul_f32_e32 v6, v17, v12
	v_cvt_pk_bf16_f32 v6, v6, v157
	ds_write_b16 v107, v6 offset:352
	v_mul_f32_e32 v6, v16, v12
	v_cvt_pk_bf16_f32 v6, v6, v157
	ds_write_b16 v107, v6 offset:496
	v_mul_f32_e32 v6, v23, v12
	v_cvt_pk_bf16_f32 v6, v6, v157
	ds_write_b16 v107, v6 offset:640
	v_mul_f32_e32 v6, v22, v12
	v_cvt_pk_bf16_f32 v6, v6, v157
	ds_write_b16 v107, v6 offset:784
	v_mul_f32_e32 v6, v31, v12
	v_cvt_pk_bf16_f32 v6, v6, v157
	ds_write_b16 v107, v6 offset:928
	v_mul_f32_e32 v6, v30, v12
	v_cvt_pk_bf16_f32 v6, v6, v157
	ds_write_b16 v107, v6 offset:1072
	v_or_b32_e32 v6, s39, v106
	v_mul_u32_u24_e32 v78, 0x90, v6
	v_and_b32_e32 v14, -16, v130
	v_mul_u32_u24_e32 v82, 0x90, v106
	s_waitcnt lgkmcnt(0)
	s_barrier
	v_bfe_u32 v6, v224, 6, 2
	v_and_b32_e32 v7, 15, v232
	v_lshrrev_b32_e32 v8, 4, v232
	v_lshl_or_b32 v9, v6, 4, v7
	v_mul_u32_u24_e32 v10, 0x90, v9
	v_mul_u32_u24_e32 v11, 0x90, v7
	v_lshl_add_u32 v13, v8, 4, v10
	v_lshl_add_u32 v11, v8, 4, v11
	v_add_u32_e32 v13, v182, v13
	v_add_u32_e32 v11, v182, v11
	v_add_u32_e32 v15, 0x4800, v13
	v_add_u32_e32 v11, 0x2400, v11
	ds_read_b128 v[16:19], v15
	ds_read_b128 v[20:23], v15 offset:64
	ds_read_b128 v[24:27], v13
	ds_read_b128 v[28:31], v13 offset:64
	ds_read_b128 v[32:35], v11
	ds_read_b128 v[36:39], v11 offset:64
	ds_read_b128 v[40:43], v11 offset:2304
	ds_read_b128 v[44:47], v11 offset:2368
	ds_read_b128 v[48:51], v11 offset:4608
	ds_read_b128 v[52:55], v11 offset:4672
	ds_read_b128 v[56:59], v11 offset:6912
	ds_read_b128 v[60:63], v11 offset:6976
	v_lshl_add_u32 v66, v9, 2, v185
	v_lshl_add_u32 v67, v8, 4, v185
	ds_read_b32 v64, v66
	ds_read_b128 v[136:139], v67
	ds_read_b128 v[140:143], v67 offset:64
	v_lshlrev_b32_e32 v12, 2, v8
	v_sub_u32_e32 v12, v9, v12
	v_lshl_add_u32 v65, v8, 3, v10
	v_add_u32_e32 v68, v186, v65
	v_add_u32_e32 v69, v184, v65
	s_waitcnt lgkmcnt(3)
	v_mfma_f32_16x16x32_bf16 v[190:193], v[32:35], v[16:19], 0
	v_mfma_f32_16x16x32_bf16 v[206:209], v[32:35], v[24:27], 0
	v_mfma_f32_16x16x32_bf16 v[194:197], v[40:43], v[16:19], 0
	v_mfma_f32_16x16x32_bf16 v[210:213], v[40:43], v[24:27], 0
	v_mfma_f32_16x16x32_bf16 v[198:201], v[48:51], v[16:19], 0
	v_mfma_f32_16x16x32_bf16 v[214:217], v[48:51], v[24:27], 0
	v_mfma_f32_16x16x32_bf16 v[202:205], v[56:59], v[16:19], 0
	v_mfma_f32_16x16x32_bf16 v[218:221], v[56:59], v[24:27], 0
	ds_read_b128 v[144:147], v67 offset:128
	ds_read_b128 v[148:151], v67 offset:192
	v_mfma_f32_16x16x32_bf16 v[190:193], v[36:39], v[20:23], v[190:193]
	v_mfma_f32_16x16x32_bf16 v[206:209], v[36:39], v[28:31], v[206:209]
	v_mfma_f32_16x16x32_bf16 v[194:197], v[44:47], v[20:23], v[194:197]
	v_mfma_f32_16x16x32_bf16 v[210:213], v[44:47], v[28:31], v[210:213]
	v_mfma_f32_16x16x32_bf16 v[198:201], v[52:55], v[20:23], v[198:201]
	v_mfma_f32_16x16x32_bf16 v[214:217], v[52:55], v[28:31], v[214:217]
	v_mfma_f32_16x16x32_bf16 v[202:205], v[60:63], v[20:23], v[202:205]
	v_mfma_f32_16x16x32_bf16 v[218:221], v[60:63], v[28:31], v[218:221]
	v_readlane_b32 s0, v252, 48
	v_readlane_b32 s1, v252, 49
	s_waitcnt lgkmcnt(0)
; __device__ __forceinline__ bf16_t f2bf(float f) { return (bf16_t)(pk2(f, 0.f) & 0xffffu); }
; __device__ __forceinline__ float fexp(float x) { return __expf(x); }
; __device__ __forceinline__ void gdn_unit(const Ctx& X, LAS unsigned char* hl, int b, int c, int h, int tid_h, int w4, int lane, int layer) {
;     ...
;         for (int ct = 0; ct < 4; ++ct)
; #pragma unroll
;             for (int j = 0; j < 4; ++j) { const int ii = 16 * w4 + 4 * q + j, col = 16 * ct + r;
;                 const float L = fexp(fminf(Gs[ii] - Gs[col], 0.f));
;                 AB[ii * LT + col] = f2bf(ii > col ? aA[ct][j] * L : 0.f);
;                 P[ii * LT + col] = f2bf(ii >= col ? aP[ct][j] * L : 0.f); }
	v_sub_f32_e32 v70, v64, v136
	v_sub_f32_e32 v71, v64, v137
	v_sub_f32_e32 v73, v64, v138
	v_sub_f32_e32 v74, v64, v139
	v_min_f32_e32 v70, 0, v70
	v_min_f32_e32 v71, 0, v71
	v_min_f32_e32 v73, 0, v73
	v_min_f32_e32 v74, 0, v74
	v_mul_f32_e32 v70, 0x3fb8aa3b, v70
	v_mul_f32_e32 v71, 0x3fb8aa3b, v71
	v_mul_f32_e32 v73, 0x3fb8aa3b, v73
	v_mul_f32_e32 v74, 0x3fb8aa3b, v74
	v_exp_f32_e32 v70, v70
	v_exp_f32_e32 v71, v71
	v_exp_f32_e32 v73, v73
	v_exp_f32_e32 v74, v74
	v_cmp_lt_i32_e32 vcc, 0, v12
	v_cmp_lt_i32_e64 s[4:5], 1, v12
	v_cmp_lt_i32_e64 s[6:7], 2, v12
	v_cmp_lt_i32_e64 s[24:25], 3, v12
	v_mul_f32_e32 v75, v190, v70
	v_mul_f32_e32 v76, v191, v71
	v_mul_f32_e32 v79, v192, v73
	v_mul_f32_e32 v80, v193, v74
	v_mul_f32_e32 v81, v206, v70
	v_mul_f32_e32 v83, v207, v71
	v_mul_f32_e32 v84, v208, v73
	v_mul_f32_e32 v114, v209, v74
	v_cndmask_b32_e32 v75, 0, v75, vcc
	v_cndmask_b32_e64 v76, 0, v76, s[4:5]
	v_cndmask_b32_e64 v79, 0, v79, s[6:7]
	v_cndmask_b32_e64 v80, 0, v80, s[24:25]
	v_cmp_le_i32_e32 vcc, 0, v12
	v_cmp_le_i32_e64 s[4:5], 1, v12
	v_cmp_le_i32_e64 s[6:7], 2, v12
	v_cmp_le_i32_e64 s[24:25], 3, v12
	v_cvt_pk_bf16_f32 v116, v75, v76
	v_cvt_pk_bf16_f32 v117, v79, v80
	ds_write_b64 v68, v[116:117]
	v_cndmask_b32_e32 v81, 0, v81, vcc
	v_cndmask_b32_e64 v83, 0, v83, s[4:5]
	v_cndmask_b32_e64 v84, 0, v84, s[6:7]
	v_cndmask_b32_e64 v114, 0, v114, s[24:25]
	v_cvt_pk_bf16_f32 v152, v81, v83
	v_cvt_pk_bf16_f32 v153, v84, v114
	ds_write_b64 v69, v[152:153]
	v_sub_f32_e32 v70, v64, v140
	v_sub_f32_e32 v71, v64, v141
	v_sub_f32_e32 v73, v64, v142
	v_sub_f32_e32 v74, v64, v143
	v_min_f32_e32 v70, 0, v70
	v_min_f32_e32 v71, 0, v71
	v_min_f32_e32 v73, 0, v73
	v_min_f32_e32 v74, 0, v74
	v_mul_f32_e32 v70, 0x3fb8aa3b, v70
	v_mul_f32_e32 v71, 0x3fb8aa3b, v71
	v_mul_f32_e32 v73, 0x3fb8aa3b, v73
	v_mul_f32_e32 v74, 0x3fb8aa3b, v74
	v_exp_f32_e32 v70, v70
	v_exp_f32_e32 v71, v71
	v_exp_f32_e32 v73, v73
	v_exp_f32_e32 v74, v74
	v_cmp_lt_i32_e32 vcc, 16, v12
	v_cmp_lt_i32_e64 s[4:5], 17, v12
	v_cmp_lt_i32_e64 s[6:7], 18, v12
	v_cmp_lt_i32_e64 s[24:25], 19, v12
	v_mul_f32_e32 v75, v194, v70
	v_mul_f32_e32 v76, v195, v71
	v_mul_f32_e32 v79, v196, v73
	v_mul_f32_e32 v80, v197, v74
	v_mul_f32_e32 v81, v210, v70
	v_mul_f32_e32 v83, v211, v71
	v_mul_f32_e32 v84, v212, v73
	v_mul_f32_e32 v114, v213, v74
	v_cndmask_b32_e32 v75, 0, v75, vcc
	v_cndmask_b32_e64 v76, 0, v76, s[4:5]
	v_cndmask_b32_e64 v79, 0, v79, s[6:7]
	v_cndmask_b32_e64 v80, 0, v80, s[24:25]
	v_cmp_le_i32_e32 vcc, 16, v12
	v_cmp_le_i32_e64 s[4:5], 17, v12
	v_cmp_le_i32_e64 s[6:7], 18, v12
	v_cmp_le_i32_e64 s[24:25], 19, v12
	v_cvt_pk_bf16_f32 v116, v75, v76
	v_cvt_pk_bf16_f32 v117, v79, v80
	ds_write_b64 v68, v[116:117] offset:32
	v_cndmask_b32_e32 v81, 0, v81, vcc
	v_cndmask_b32_e64 v83, 0, v83, s[4:5]
	v_cndmask_b32_e64 v84, 0, v84, s[6:7]
	v_cndmask_b32_e64 v114, 0, v114, s[24:25]
	v_cvt_pk_bf16_f32 v152, v81, v83
	v_cvt_pk_bf16_f32 v153, v84, v114
	ds_write_b64 v69, v[152:153] offset:32
	v_sub_f32_e32 v70, v64, v144
	v_sub_f32_e32 v71, v64, v145
	v_sub_f32_e32 v73, v64, v146
	v_sub_f32_e32 v74, v64, v147
	v_min_f32_e32 v70, 0, v70
	v_min_f32_e32 v71, 0, v71
	v_min_f32_e32 v73, 0, v73
	v_min_f32_e32 v74, 0, v74
	v_mul_f32_e32 v70, 0x3fb8aa3b, v70
	v_mul_f32_e32 v71, 0x3fb8aa3b, v71
	v_mul_f32_e32 v73, 0x3fb8aa3b, v73
	v_mul_f32_e32 v74, 0x3fb8aa3b, v74
	v_exp_f32_e32 v70, v70
	v_exp_f32_e32 v71, v71
	v_exp_f32_e32 v73, v73
	v_exp_f32_e32 v74, v74
	v_cmp_lt_i32_e32 vcc, 32, v12
	v_cmp_lt_i32_e64 s[4:5], 33, v12
	v_cmp_lt_i32_e64 s[6:7], 34, v12
	v_cmp_lt_i32_e64 s[24:25], 35, v12
	v_mul_f32_e32 v75, v198, v70
	v_mul_f32_e32 v76, v199, v71
	v_mul_f32_e32 v79, v200, v73
	v_mul_f32_e32 v80, v201, v74
	v_mul_f32_e32 v81, v214, v70
	v_mul_f32_e32 v83, v215, v71
	v_mul_f32_e32 v84, v216, v73
	v_mul_f32_e32 v114, v217, v74
	v_cndmask_b32_e32 v75, 0, v75, vcc
	v_cndmask_b32_e64 v76, 0, v76, s[4:5]
	v_cndmask_b32_e64 v79, 0, v79, s[6:7]
	v_cndmask_b32_e64 v80, 0, v80, s[24:25]
	v_cmp_le_i32_e32 vcc, 32, v12
	v_cmp_le_i32_e64 s[4:5], 33, v12
	v_cmp_le_i32_e64 s[6:7], 34, v12
	v_cmp_le_i32_e64 s[24:25], 35, v12
	v_cvt_pk_bf16_f32 v116, v75, v76
	v_cvt_pk_bf16_f32 v117, v79, v80
	ds_write_b64 v68, v[116:117] offset:64
	v_cndmask_b32_e32 v81, 0, v81, vcc
	v_cndmask_b32_e64 v83, 0, v83, s[4:5]
	v_cndmask_b32_e64 v84, 0, v84, s[6:7]
	v_cndmask_b32_e64 v114, 0, v114, s[24:25]
	v_cvt_pk_bf16_f32 v152, v81, v83
	v_cvt_pk_bf16_f32 v153, v84, v114
	ds_write_b64 v69, v[152:153] offset:64
	v_sub_f32_e32 v70, v64, v148
	v_sub_f32_e32 v71, v64, v149
	v_sub_f32_e32 v73, v64, v150
	v_sub_f32_e32 v74, v64, v151
	v_min_f32_e32 v70, 0, v70
	v_min_f32_e32 v71, 0, v71
	v_min_f32_e32 v73, 0, v73
	v_min_f32_e32 v74, 0, v74
	v_mul_f32_e32 v70, 0x3fb8aa3b, v70
	v_mul_f32_e32 v71, 0x3fb8aa3b, v71
	v_mul_f32_e32 v73, 0x3fb8aa3b, v73
	v_mul_f32_e32 v74, 0x3fb8aa3b, v74
	v_exp_f32_e32 v70, v70
	v_exp_f32_e32 v71, v71
	v_exp_f32_e32 v73, v73
	v_exp_f32_e32 v74, v74
	v_cmp_lt_i32_e32 vcc, 48, v12
	v_cmp_lt_i32_e64 s[4:5], 49, v12
	v_cmp_lt_i32_e64 s[6:7], 50, v12
	v_cmp_lt_i32_e64 s[24:25], 51, v12
	v_mul_f32_e32 v75, v202, v70
	v_mul_f32_e32 v76, v203, v71
	v_mul_f32_e32 v79, v204, v73
	v_mul_f32_e32 v80, v205, v74
	v_mul_f32_e32 v81, v218, v70
	v_mul_f32_e32 v83, v219, v71
	v_mul_f32_e32 v84, v220, v73
	v_mul_f32_e32 v114, v221, v74
	v_cndmask_b32_e32 v75, 0, v75, vcc
	v_cndmask_b32_e64 v76, 0, v76, s[4:5]
	v_cndmask_b32_e64 v79, 0, v79, s[6:7]
	v_cndmask_b32_e64 v80, 0, v80, s[24:25]
	v_cmp_le_i32_e32 vcc, 48, v12
	v_cmp_le_i32_e64 s[4:5], 49, v12
	v_cmp_le_i32_e64 s[6:7], 50, v12
	v_cmp_le_i32_e64 s[24:25], 51, v12
	v_cvt_pk_bf16_f32 v116, v75, v76
	v_cvt_pk_bf16_f32 v117, v79, v80
	ds_write_b64 v68, v[116:117] offset:96
	v_cndmask_b32_e32 v81, 0, v81, vcc
	v_cndmask_b32_e64 v83, 0, v83, s[4:5]
	v_cndmask_b32_e64 v84, 0, v84, s[6:7]
	v_cndmask_b32_e64 v114, 0, v114, s[24:25]
	v_cvt_pk_bf16_f32 v152, v81, v83
	v_cvt_pk_bf16_f32 v153, v84, v114
	ds_write_b64 v69, v[152:153] offset:96
	s_branch .Lgdn_s2_pad_end
; #define LAS __attribute__((address_space(3)))
; __device__ __forceinline__ float bf2f(bf16_t b) { return __uint_as_float((unsigned)b << 16); }
; __device__ __forceinline__ float fexp(float x) { return __expf(x); }
; #define LBAR() do { asm volatile("s_waitcnt lgkmcnt(0)" ::: "memory"); __builtin_amdgcn_s_barrier(); asm volatile("" ::: "memory"); } while (0)
; __device__ __forceinline__ void gdn_unit(const Ctx& X, LAS unsigned char* hl, int b, int c, int h, int tid_h, int w4, int lane, int layer) {
;     ...
;     LBAR();
;     float rc[64];
;     if (w4 < 2) {
;         const int col = tid_h & 63; const LAS bf16_t* src = w4 == 0 ? V : KB;
; #pragma unroll
;         for (int i = 0; i < 64; ++i) { const float sc = w4 == 0 ? Bs[i] : fexp(Gs[i]); rc[i] = bf2f(src[i * LT + col]) * sc; }
;     }
	s_nop 0
	s_nop 0
	s_nop 0
	s_nop 0
	s_nop 0
	s_nop 0
	s_nop 0
	s_nop 0
	s_nop 0
	s_nop 0
	s_nop 0
	s_nop 0
	s_nop 0
	s_nop 0
	s_nop 0
	s_nop 0
	s_nop 0
	s_nop 0
	s_nop 0
	s_nop 0
	s_nop 0
	s_nop 0
	s_nop 0
	s_nop 0
	s_nop 0
	s_nop 0
	s_nop 0
	s_nop 0
	s_nop 0
	s_nop 0
	s_nop 0
	s_nop 0
	s_nop 0
	s_nop 0
	s_nop 0
	s_nop 0
	s_nop 0
	s_nop 0
	s_nop 0
	s_nop 0
	s_nop 0
	s_nop 0
	s_nop 0
	s_nop 0
	s_nop 0
	s_nop 0
	s_nop 0
	s_nop 0
	s_nop 0
	s_nop 0
	s_nop 0
	s_nop 0
	s_nop 0
	s_nop 0
	s_nop 0
	s_nop 0
	s_nop 0
	s_nop 0
	s_nop 0
	s_nop 0
	s_nop 0
	s_nop 0
	s_nop 0
	s_nop 0
	s_nop 0
	s_nop 0
	s_nop 0
	s_nop 0
	s_nop 0
	s_nop 0
	s_nop 0
	s_nop 0
	s_nop 0
	s_nop 0
	s_nop 0
	s_nop 0
	s_nop 0
	s_nop 0
	s_nop 0
	s_nop 0
	s_nop 0
	s_nop 0
	s_nop 0
	s_nop 0
	s_nop 0
	s_nop 0
	s_nop 0
	s_nop 0
	s_nop 0
	s_nop 0
	s_nop 0
	s_nop 0
	s_nop 0
	s_nop 0
	s_nop 0
	s_nop 0
	s_nop 0
	s_nop 0
	s_nop 0
	s_nop 0
	s_nop 0
	s_nop 0
	s_nop 0
	s_nop 0
	s_nop 0
	s_nop 0
	s_nop 0
	s_nop 0
	s_nop 0
	s_nop 0
	s_nop 0
	s_nop 0
	s_nop 0
	s_nop 0
	s_nop 0
	s_nop 0
	s_nop 0
	s_nop 0
	s_nop 0
	s_nop 0
	s_nop 0
	s_nop 0
	s_nop 0
	s_nop 0
	s_nop 0
	s_nop 0
	s_nop 0
	s_nop 0
	s_nop 0
	s_nop 0
	s_nop 0
	s_nop 0
	s_nop 0
	s_nop 0
	s_nop 0
	s_nop 0
	s_nop 0
	s_nop 0
	s_nop 0
	s_nop 0
	s_nop 0
	s_nop 0
	s_nop 0
	s_nop 0
	s_nop 0
.Lgdn_s2_pad_end:
	s_waitcnt lgkmcnt(0)
	s_barrier
	v_cndmask_b32_e64 v6, 0, 1, s[0:1]
	v_cmp_ne_u32_e64 s[4:5], 1, v6
	s_andn2_b64 vcc, exec, s[0:1]
	s_cbranch_vccnz .LBB0_608
	v_readlane_b32 s6, v252, 46
	v_readlane_b32 s7, v252, 47
	v_and_b32_e32 v7, 63, v132
	v_cndmask_b32_e64 v8, v183, v181, s[40:41]
	v_lshl_add_u32 v8, v7, 1, v8
	s_and_b64 vcc, exec, s[6:7]
	s_cbranch_vccz .Lrc_bs
	ds_read_b32 v6, v185
	ds_read_b32 v9, v185 offset:4
	ds_read_b32 v11, v185 offset:8
	ds_read_b32 v13, v185 offset:12
	ds_read_b32 v15, v185 offset:16
	ds_read_b32 v17, v185 offset:20
	ds_read_b32 v19, v185 offset:24
	ds_read_b32 v26, v185 offset:28
	ds_read_b32 v29, v185 offset:32
	ds_read_b32 v32, v185 offset:36
	ds_read_b32 v30, v185 offset:40
	ds_read_b32 v35, v185 offset:44
	ds_read_b32 v28, v185 offset:48
	ds_read_b32 v38, v185 offset:52
	ds_read_b32 v40, v185 offset:56
	ds_read_b32 v42, v185 offset:60
	ds_read_b32 v25, v185 offset:64
	ds_read_b32 v45, v185 offset:68
	ds_read_b32 v47, v185 offset:72
	ds_read_b32 v49, v185 offset:76
	ds_read_b32 v51, v185 offset:80
	ds_read_b32 v53, v185 offset:84
	ds_read_b32 v55, v185 offset:88
	ds_read_b32 v57, v185 offset:92
	ds_read_b32 v59, v185 offset:96
	ds_read_b32 v61, v185 offset:100
	ds_read_b32 v63, v185 offset:104
	ds_read_b32 v65, v185 offset:108
	ds_read_b32 v67, v185 offset:112
	ds_read_b32 v69, v185 offset:116
	ds_read_b32 v71, v185 offset:120
	ds_read_b32 v24, v185 offset:124
	ds_read_b32 v23, v185 offset:128
	ds_read_b32 v113, v185 offset:132
	ds_read_b32 v112, v185 offset:136
	ds_read_b32 v111, v185 offset:140
	ds_read_b32 v110, v185 offset:144
	ds_read_b32 v109, v185 offset:148
	ds_read_b32 v108, v185 offset:152
	ds_read_b32 v107, v185 offset:156
	ds_read_b32 v105, v185 offset:160
	ds_read_b32 v104, v185 offset:164
	ds_read_b32 v103, v185 offset:168
	ds_read_b32 v102, v185 offset:172
	ds_read_b32 v101, v185 offset:176
	ds_read_b32 v100, v185 offset:180
	ds_read_b32 v99, v185 offset:184
	ds_read_b32 v22, v185 offset:188
	ds_read_b32 v21, v185 offset:192
	ds_read_b32 v98, v185 offset:196
	ds_read_b32 v97, v185 offset:200
	ds_read_b32 v96, v185 offset:204
	ds_read_b32 v95, v185 offset:208
	ds_read_b32 v94, v185 offset:212
	ds_read_b32 v93, v185 offset:216
	ds_read_b32 v92, v185 offset:220
	ds_read_b32 v91, v185 offset:224
	ds_read_b32 v90, v185 offset:228
	ds_read_b32 v89, v185 offset:232
	ds_read_b32 v88, v185 offset:236
	ds_read_b32 v87, v185 offset:240
	ds_read_b32 v86, v185 offset:244
	ds_read_b32 v85, v185 offset:248
	ds_read_b32 v144, v185 offset:252
	ds_read_u16 v7, v8
	ds_read_u16 v10, v8 offset:144
	ds_read_u16 v12, v8 offset:288
	ds_read_u16 v14, v8 offset:432
	ds_read_u16 v16, v8 offset:576
	ds_read_u16 v18, v8 offset:720
	ds_read_u16 v20, v8 offset:864
	ds_read_u16 v27, v8 offset:1008
	ds_read_u16 v31, v8 offset:1152
	ds_read_u16 v33, v8 offset:1296
	ds_read_u16 v34, v8 offset:1440
	ds_read_u16 v36, v8 offset:1584
	ds_read_u16 v37, v8 offset:1728
	ds_read_u16 v39, v8 offset:1872
	ds_read_u16 v41, v8 offset:2016
	ds_read_u16 v43, v8 offset:2160
	ds_read_u16 v44, v8 offset:2304
	ds_read_u16 v46, v8 offset:2448
	ds_read_u16 v48, v8 offset:2592
	ds_read_u16 v50, v8 offset:2736
	ds_read_u16 v52, v8 offset:2880
	ds_read_u16 v54, v8 offset:3024
	ds_read_u16 v56, v8 offset:3168
	ds_read_u16 v58, v8 offset:3312
	ds_read_u16 v60, v8 offset:3456
	ds_read_u16 v62, v8 offset:3600
	ds_read_u16 v64, v8 offset:3744
	ds_read_u16 v66, v8 offset:3888
	ds_read_u16 v68, v8 offset:4032
	ds_read_u16 v70, v8 offset:4176
	ds_read_u16 v84, v8 offset:4320
	ds_read_u16 v114, v8 offset:4464
	ds_read_u16 v115, v8 offset:4608
	ds_read_u16 v116, v8 offset:4752
	ds_read_u16 v117, v8 offset:4896
	ds_read_u16 v118, v8 offset:5040
	ds_read_u16 v119, v8 offset:5184
	ds_read_u16 v120, v8 offset:5328
	ds_read_u16 v121, v8 offset:5472
	ds_read_u16 v122, v8 offset:5616
	ds_read_u16 v123, v8 offset:5760
	ds_read_u16 v124, v8 offset:5904
	ds_read_u16 v125, v8 offset:6048
	ds_read_u16 v126, v8 offset:6192
	ds_read_u16 v127, v8 offset:6336
	ds_read_u16 v128, v8 offset:6480
	ds_read_u16 v129, v8 offset:6624
	ds_read_u16 v133, v8 offset:6768
	ds_read_u16 v134, v8 offset:6912
	ds_read_u16 v135, v8 offset:7056
	ds_read_u16 v136, v8 offset:7200
	ds_read_u16 v137, v8 offset:7344
	ds_read_u16 v138, v8 offset:7488
	ds_read_u16 v139, v8 offset:7632
	ds_read_u16 v140, v8 offset:7776
	ds_read_u16 v141, v8 offset:7920
	ds_read_u16 v142, v8 offset:8064
	ds_read_u16 v143, v8 offset:8208
	ds_read_u16 v145, v8 offset:8352
	ds_read_u16 v146, v8 offset:8496
	ds_read_u16 v147, v8 offset:8640
	ds_read_u16 v148, v8 offset:8784
	ds_read_u16 v149, v8 offset:8928
	s_waitcnt lgkmcnt(15)
; #define LAS __attribute__((address_space(3)))
; __device__ __forceinline__ float bf2f(bf16_t b) { return __uint_as_float((unsigned)b << 16); }
; __device__ __forceinline__ float fexp(float x) { return __expf(x); }
; __device__ __forceinline__ void gdn_unit(const Ctx& X, LAS unsigned char* hl, int b, int c, int h, int tid_h, int w4, int lane, int layer) {
;     ...
;     if (w4 < 2) {
;         const int col = tid_h & 63; const LAS bf16_t* src = w4 == 0 ? V : KB;
; #pragma unroll
;         for (int i = 0; i < 64; ++i) { const float sc = w4 == 0 ? Bs[i] : fexp(Gs[i]); rc[i] = bf2f(src[i * LT + col]) * sc; }
;     }
	v_mul_f32_e32 v6, 0x3fb8aa3b, v6
	v_exp_f32_e32 v6, v6
	v_mul_f32_e32 v9, 0x3fb8aa3b, v9
	v_exp_f32_e32 v9, v9
	v_mul_f32_e32 v11, 0x3fb8aa3b, v11
	v_exp_f32_e32 v11, v11
	v_mul_f32_e32 v13, 0x3fb8aa3b, v13
	v_exp_f32_e32 v13, v13
	v_mul_f32_e32 v15, 0x3fb8aa3b, v15
	v_exp_f32_e32 v15, v15
	v_mul_f32_e32 v17, 0x3fb8aa3b, v17
	v_exp_f32_e32 v17, v17
	v_mul_f32_e32 v19, 0x3fb8aa3b, v19
	v_exp_f32_e32 v19, v19
	v_mul_f32_e32 v26, 0x3fb8aa3b, v26
	v_exp_f32_e32 v26, v26
	v_mul_f32_e32 v29, 0x3fb8aa3b, v29
	v_exp_f32_e32 v29, v29
	v_mul_f32_e32 v32, 0x3fb8aa3b, v32
	v_exp_f32_e32 v32, v32
	v_mul_f32_e32 v30, 0x3fb8aa3b, v30
	v_exp_f32_e32 v30, v30
	v_mul_f32_e32 v35, 0x3fb8aa3b, v35
	v_exp_f32_e32 v35, v35
	v_mul_f32_e32 v28, 0x3fb8aa3b, v28
	v_exp_f32_e32 v28, v28
	v_mul_f32_e32 v38, 0x3fb8aa3b, v38
	v_exp_f32_e32 v38, v38
	v_mul_f32_e32 v40, 0x3fb8aa3b, v40
	v_exp_f32_e32 v40, v40
	v_mul_f32_e32 v42, 0x3fb8aa3b, v42
	v_exp_f32_e32 v42, v42
	v_mul_f32_e32 v25, 0x3fb8aa3b, v25
	v_exp_f32_e32 v25, v25
	v_mul_f32_e32 v45, 0x3fb8aa3b, v45
	v_exp_f32_e32 v45, v45
	v_mul_f32_e32 v47, 0x3fb8aa3b, v47
	v_exp_f32_e32 v47, v47
	v_mul_f32_e32 v49, 0x3fb8aa3b, v49
	v_exp_f32_e32 v49, v49
	v_mul_f32_e32 v51, 0x3fb8aa3b, v51
	v_exp_f32_e32 v51, v51
	v_mul_f32_e32 v53, 0x3fb8aa3b, v53
	v_exp_f32_e32 v53, v53
	v_mul_f32_e32 v55, 0x3fb8aa3b, v55
	v_exp_f32_e32 v55, v55
	v_mul_f32_e32 v57, 0x3fb8aa3b, v57
	v_exp_f32_e32 v57, v57
	v_mul_f32_e32 v59, 0x3fb8aa3b, v59
	v_exp_f32_e32 v59, v59
	v_mul_f32_e32 v61, 0x3fb8aa3b, v61
	v_exp_f32_e32 v61, v61
	v_mul_f32_e32 v63, 0x3fb8aa3b, v63
	v_exp_f32_e32 v63, v63
	v_mul_f32_e32 v65, 0x3fb8aa3b, v65
	v_exp_f32_e32 v65, v65
	v_mul_f32_e32 v67, 0x3fb8aa3b, v67
	v_exp_f32_e32 v67, v67
	v_mul_f32_e32 v69, 0x3fb8aa3b, v69
	v_exp_f32_e32 v69, v69
	v_mul_f32_e32 v71, 0x3fb8aa3b, v71
	v_exp_f32_e32 v71, v71
	v_mul_f32_e32 v24, 0x3fb8aa3b, v24
	v_exp_f32_e32 v24, v24
	v_mul_f32_e32 v23, 0x3fb8aa3b, v23
	v_exp_f32_e32 v23, v23
	v_mul_f32_e32 v113, 0x3fb8aa3b, v113
	v_exp_f32_e32 v113, v113
	v_mul_f32_e32 v112, 0x3fb8aa3b, v112
	v_exp_f32_e32 v112, v112
	v_mul_f32_e32 v111, 0x3fb8aa3b, v111
	v_exp_f32_e32 v111, v111
	v_mul_f32_e32 v110, 0x3fb8aa3b, v110
	v_exp_f32_e32 v110, v110
	v_mul_f32_e32 v109, 0x3fb8aa3b, v109
	v_exp_f32_e32 v109, v109
	v_mul_f32_e32 v108, 0x3fb8aa3b, v108
	v_exp_f32_e32 v108, v108
	v_mul_f32_e32 v107, 0x3fb8aa3b, v107
	v_exp_f32_e32 v107, v107
	v_mul_f32_e32 v105, 0x3fb8aa3b, v105
	v_exp_f32_e32 v105, v105
	v_mul_f32_e32 v104, 0x3fb8aa3b, v104
	v_exp_f32_e32 v104, v104
	v_mul_f32_e32 v103, 0x3fb8aa3b, v103
	v_exp_f32_e32 v103, v103
	v_mul_f32_e32 v102, 0x3fb8aa3b, v102
	v_exp_f32_e32 v102, v102
	v_mul_f32_e32 v101, 0x3fb8aa3b, v101
	v_exp_f32_e32 v101, v101
	v_mul_f32_e32 v100, 0x3fb8aa3b, v100
	v_exp_f32_e32 v100, v100
	v_mul_f32_e32 v99, 0x3fb8aa3b, v99
	v_exp_f32_e32 v99, v99
	v_mul_f32_e32 v22, 0x3fb8aa3b, v22
	v_exp_f32_e32 v22, v22
	v_mul_f32_e32 v21, 0x3fb8aa3b, v21
	v_exp_f32_e32 v21, v21
	v_mul_f32_e32 v98, 0x3fb8aa3b, v98
	v_exp_f32_e32 v98, v98
	v_mul_f32_e32 v97, 0x3fb8aa3b, v97
	v_exp_f32_e32 v97, v97
	v_mul_f32_e32 v96, 0x3fb8aa3b, v96
	v_exp_f32_e32 v96, v96
	v_mul_f32_e32 v95, 0x3fb8aa3b, v95
	v_exp_f32_e32 v95, v95
	v_mul_f32_e32 v94, 0x3fb8aa3b, v94
	v_exp_f32_e32 v94, v94
	v_mul_f32_e32 v93, 0x3fb8aa3b, v93
	v_exp_f32_e32 v93, v93
	v_mul_f32_e32 v92, 0x3fb8aa3b, v92
	v_exp_f32_e32 v92, v92
	v_mul_f32_e32 v91, 0x3fb8aa3b, v91
	v_exp_f32_e32 v91, v91
	v_mul_f32_e32 v90, 0x3fb8aa3b, v90
	v_exp_f32_e32 v90, v90
	v_mul_f32_e32 v89, 0x3fb8aa3b, v89
	v_exp_f32_e32 v89, v89
	v_mul_f32_e32 v88, 0x3fb8aa3b, v88
	v_exp_f32_e32 v88, v88
	v_mul_f32_e32 v87, 0x3fb8aa3b, v87
	v_exp_f32_e32 v87, v87
	v_mul_f32_e32 v86, 0x3fb8aa3b, v86
	v_exp_f32_e32 v86, v86
	v_mul_f32_e32 v85, 0x3fb8aa3b, v85
	v_exp_f32_e32 v85, v85
	v_mul_f32_e32 v144, 0x3fb8aa3b, v144
	v_exp_f32_e32 v144, v144
	s_branch .Lrc_join
